# v51 + sc1 (L2-bypass) on the 32 residual base loads of each residual-norm epilogue (P2,P8,P10)
# baseline (speedup 1.0000x reference)
.LBB0_232:
	v_lshl_add_u32 v64, s54, 8, v216
	v_lshl_or_b32 v140, s55, 8, v218
	v_ashrrev_i32_e32 v65, 31, v64
	v_readlane_b32 s60, v252, 0
	v_ashrrev_i32_e32 v141, 31, v140
	s_waitcnt lgkmcnt(0)
	v_lshlrev_b64 v[0:1], 13, v[64:65]
	v_readlane_b32 s61, v252, 1
	v_lshlrev_b64 v[16:17], 2, v[140:141]
	v_readlane_b32 s74, v252, 14
	v_lshl_add_u64 v[212:213], s[60:61], 0, v[0:1]
	v_lshl_add_u64 v[0:1], v[212:213], 0, v[16:17]
	v_readlane_b32 s75, v252, 15
	global_load_dwordx4 v[28:31], v[0:1], off sc1
	global_load_dwordx4 v[40:43], v[0:1], off offset:64 sc1
	global_load_dwordx4 v[52:55], v[0:1], off offset:512 sc1
	v_lshl_add_u64 v[2:3], s[74:75], 0, v[16:17]
	global_load_dwordx4 v[12:15], v[2:3], off
	global_load_dwordx4 v[8:11], v[2:3], off offset:64
	global_load_dwordx4 v[4:7], v[2:3], off offset:512
	global_load_dwordx4 v[60:63], v[0:1], off offset:576 sc1
	v_or_b32_e32 v66, 16, v64
	v_or_b32_e32 v214, 32, v64
	v_ashrrev_i32_e32 v67, 31, v66
	v_ashrrev_i32_e32 v215, 31, v214
	v_lshlrev_b64 v[18:19], 13, v[66:67]
	v_lshlrev_b64 v[20:21], 13, v[214:215]
	v_lshl_add_u64 v[18:19], s[60:61], 0, v[18:19]
	v_lshl_add_u64 v[20:21], s[60:61], 0, v[20:21]
	global_load_dwordx4 v[0:3], v[2:3], off offset:576
	v_lshl_add_u64 v[18:19], v[18:19], 0, v[16:17]
	v_lshl_add_u64 v[16:17], v[20:21], 0, v[16:17]
	global_load_dwordx4 v[56:59], v[18:19], off sc1
	global_load_dwordx4 v[48:51], v[18:19], off offset:64 sc1
	global_load_dwordx4 v[36:39], v[18:19], off offset:512 sc1
	global_load_dwordx4 v[24:27], v[18:19], off offset:576 sc1
	global_load_dwordx4 v[44:47], v[16:17], off sc1
	global_load_dwordx4 v[32:35], v[16:17], off offset:64 sc1
	global_load_dwordx4 v[20:23], v[16:17], off offset:512 sc1
	s_nop 0
	global_load_dwordx4 v[16:19], v[16:17], off offset:576 sc1
	v_and_b32_e32 v225, 64, v223
	v_xor_b32_e32 v224, 16, v223
	v_add_u32_e32 v225, 64, v225
	v_xor_b32_e32 v226, 32, v223
	v_cmp_lt_i32_e32 vcc, v224, v225
	v_readlane_b32 s62, v252, 2
	v_readlane_b32 s63, v252, 3
	v_readlane_b32 s64, v252, 4
	v_readlane_b32 s65, v252, 5
	v_readlane_b32 s66, v252, 6
	v_readlane_b32 s67, v252, 7
	v_readlane_b32 s68, v252, 8
	v_readlane_b32 s69, v252, 9
	v_readlane_b32 s70, v252, 10
	v_readlane_b32 s71, v252, 11
	v_readlane_b32 s72, v252, 12
	v_readlane_b32 s73, v252, 13
	v_cndmask_b32_e32 v224, v223, v224, vcc
	v_cmp_lt_i32_e32 vcc, v226, v225
	v_readlane_b32 s60, v252, 16
	v_readlane_b32 s74, v252, 30
	v_cndmask_b32_e32 v228, v223, v226, vcc
	v_lshlrev_b64 v[226:227], 11, v[64:65]
	v_lshl_add_u64 v[226:227], v[226:227], 0, v[140:141]
	v_readlane_b32 s75, v252, 31
	v_lshlrev_b32_e32 v225, 2, v224
	v_lshlrev_b32_e32 v224, 2, v228
	v_lshl_add_u64 v[228:229], v[226:227], 2, s[74:75]
	v_lshlrev_b64 v[226:227], 1, v[226:227]
	v_lshl_add_u64 v[230:231], s[12:13], 0, v[226:227]
	v_or_b32_e32 v232, 32, v226
	v_mov_b32_e32 v233, v227
	v_lshl_add_u64 v[232:233], s[12:13], 0, v[232:233]
	v_readlane_b32 s61, v252, 17
	v_readlane_b32 s62, v252, 18
	v_readlane_b32 s63, v252, 19
	v_readlane_b32 s64, v252, 20
	v_readlane_b32 s65, v252, 21
	v_readlane_b32 s66, v252, 22
	v_readlane_b32 s67, v252, 23
	v_readlane_b32 s68, v252, 24
	v_readlane_b32 s69, v252, 25
	v_readlane_b32 s70, v252, 26
	v_readlane_b32 s71, v252, 27
	v_readlane_b32 s72, v252, 28
	v_readlane_b32 s73, v252, 29
	s_waitcnt vmcnt(0)
	v_pk_add_f32 v[30:31], v[200:201], v[30:31]
	v_pk_add_f32 v[28:29], v[202:203], v[28:29]
	v_pk_add_f32 v[42:43], v[204:205], v[42:43]
	v_pk_add_f32 v[40:41], v[206:207], v[40:41]
	v_pk_add_f32 v[54:55], v[210:211], v[54:55]
	v_pk_add_f32 v[52:53], v[208:209], v[52:53]
	v_mul_f32_e32 v234, v29, v29
	v_mul_f32_e32 v235, v31, v31
	v_pk_mul_f32 v[200:201], v[14:15], v[30:31]
	v_pk_mul_f32 v[202:203], v[12:13], v[28:29]
	v_mul_f32_e32 v236, v41, v41
	v_mul_f32_e32 v237, v43, v43
	global_store_dwordx4 v[228:229], v[28:31], off
	v_pk_mul_f32 v[204:205], v[10:11], v[42:43]
	v_pk_mul_f32 v[206:207], v[8:9], v[40:41]
	v_mul_f32_e32 v238, v53, v53
	v_mul_f32_e32 v239, v55, v55
	v_fmac_f32_e32 v234, v28, v28
	v_fmac_f32_e32 v235, v30, v30
	v_cvt_pk_bf16_f32 v28, v202, v203
	v_cvt_pk_bf16_f32 v29, v200, v201
	v_fmac_f32_e32 v236, v40, v40
	v_fmac_f32_e32 v237, v42, v42
	v_cvt_pk_bf16_f32 v30, v206, v207
	v_cvt_pk_bf16_f32 v31, v204, v205
	v_fmac_f32_e32 v238, v52, v52
	v_fmac_f32_e32 v239, v54, v54
	v_add_f32_e32 v200, v234, v235
	global_store_dwordx2 v[230:231], v[28:29], off
	global_store_dwordx4 v[228:229], v[40:43], off offset:64
	v_add_f32_e32 v28, v236, v237
	v_pk_mul_f32 v[208:209], v[6:7], v[54:55]
	v_pk_mul_f32 v[210:211], v[4:5], v[52:53]
	global_store_dwordx2 v[232:233], v[30:31], off
	global_store_dwordx4 v[228:229], v[52:55], off offset:512
	v_add_f32_e32 v29, v238, v239
	v_add_f32_e32 v28, v200, v28
	v_or_b32_e32 v30, 0x100, v226
	v_mov_b32_e32 v31, v227
	v_add_f32_e32 v40, v28, v29
	v_cvt_pk_bf16_f32 v28, v210, v211
	v_cvt_pk_bf16_f32 v29, v208, v209
	v_lshl_add_u64 v[30:31], s[12:13], 0, v[30:31]
	global_store_dwordx2 v[30:31], v[28:29], off
	v_pk_add_f32 v[30:31], v[198:199], v[62:63]
	v_pk_add_f32 v[28:29], v[196:197], v[60:61]
	v_mul_f32_e32 v42, v31, v31
	v_mul_f32_e32 v41, v29, v29
	v_fmac_f32_e32 v41, v28, v28
	v_fmac_f32_e32 v42, v30, v30
	v_add_f32_e32 v41, v41, v42
	v_add_f32_e32 v41, v40, v41
	ds_bpermute_b32 v42, v225, v41
	global_store_dwordx4 v[228:229], v[28:31], off offset:576
	v_or_b32_e32 v226, 0x120, v226
	s_nop 0
	v_pk_mul_f32 v[28:29], v[0:1], v[28:29]
	v_pk_mul_f32 v[30:31], v[2:3], v[30:31]
	v_cvt_pk_bf16_f32 v40, v28, v29
	s_waitcnt lgkmcnt(0)
	v_add_f32_e32 v28, v41, v42
	ds_bpermute_b32 v29, v224, v28
	v_cvt_pk_bf16_f32 v41, v30, v31
	v_lshl_add_u64 v[30:31], s[12:13], 0, v[226:227]
	global_store_dwordx2 v[30:31], v[40:41], off
	s_and_saveexec_b64 s[24:25], s[4:5]
	s_cbranch_execz .LBB0_234
	v_lshl_add_u64 v[30:31], v[64:65], 2, s[14:15]
	s_waitcnt lgkmcnt(0)
	v_add_f32_e32 v28, v28, v29
	global_atomic_add_f32 v[30:31], v28, off
.LBB0_234:
	s_or_b64 exec, exec, s[24:25]
	v_or_b32_e32 v196, 48, v64
	v_ashrrev_i32_e32 v197, 31, v196
	v_readlane_b32 s60, v252, 0
	s_waitcnt lgkmcnt(0)
	v_lshlrev_b64 v[28:29], 13, v[196:197]
	v_readlane_b32 s61, v252, 1
	v_readlane_b32 s62, v252, 2
	v_readlane_b32 s63, v252, 3
	v_lshl_add_u64 v[28:29], s[60:61], 0, v[28:29]
	v_lshl_add_u64 v[28:29], v[140:141], 2, v[28:29]
	global_load_dwordx4 v[60:63], v[28:29], off sc1
	global_load_dwordx4 v[52:55], v[28:29], off offset:64 sc1
	global_load_dwordx4 v[40:43], v[28:29], off offset:512 sc1
	s_nop 0
	global_load_dwordx4 v[28:31], v[28:29], off offset:576 sc1
	v_readlane_b32 s64, v252, 4
	v_readlane_b32 s65, v252, 5
	v_readlane_b32 s66, v252, 6
	v_readlane_b32 s67, v252, 7
	v_readlane_b32 s68, v252, 8
	v_readlane_b32 s69, v252, 9
	v_readlane_b32 s70, v252, 10
	v_readlane_b32 s71, v252, 11
	v_readlane_b32 s72, v252, 12
	v_readlane_b32 s73, v252, 13
	v_readlane_b32 s74, v252, 14
	v_readlane_b32 s75, v252, 15
	v_lshlrev_b64 v[198:199], 11, v[66:67]
	v_readlane_b32 s60, v252, 16
	v_lshl_add_u64 v[198:199], v[198:199], 0, v[140:141]
	v_pk_add_f32 v[58:59], v[194:195], v[58:59]
	v_pk_add_f32 v[56:57], v[192:193], v[56:57]
	v_readlane_b32 s74, v252, 30
	v_readlane_b32 s75, v252, 31
	v_mul_f32_e32 v65, v57, v57
	v_mul_f32_e32 v194, v59, v59
	v_lshl_add_u64 v[192:193], v[198:199], 2, s[74:75]
	global_store_dwordx4 v[192:193], v[56:59], off
	v_fmac_f32_e32 v65, v56, v56
	v_fmac_f32_e32 v194, v58, v58
	v_pk_mul_f32 v[58:59], v[14:15], v[58:59]
	v_pk_mul_f32 v[56:57], v[12:13], v[56:57]
	v_add_f32_e32 v65, v65, v194
	v_cvt_pk_bf16_f32 v56, v56, v57
	v_cvt_pk_bf16_f32 v57, v58, v59
	v_lshlrev_b64 v[58:59], 1, v[198:199]
	v_lshl_add_u64 v[194:195], s[12:13], 0, v[58:59]
	v_pk_add_f32 v[50:51], v[190:191], v[50:51]
	v_pk_add_f32 v[48:49], v[188:189], v[48:49]
	global_store_dwordx2 v[194:195], v[56:57], off
	v_mul_f32_e32 v56, v49, v49
	v_mul_f32_e32 v57, v51, v51
	global_store_dwordx4 v[192:193], v[48:51], off offset:64
	v_fmac_f32_e32 v56, v48, v48
	v_fmac_f32_e32 v57, v50, v50
	v_pk_mul_f32 v[50:51], v[10:11], v[50:51]
	v_pk_mul_f32 v[48:49], v[8:9], v[48:49]
	v_pk_add_f32 v[38:39], v[186:187], v[38:39]
	v_cvt_pk_bf16_f32 v48, v48, v49
	v_cvt_pk_bf16_f32 v49, v50, v51
	v_or_b32_e32 v50, 32, v58
	v_mov_b32_e32 v51, v59
	v_lshl_add_u64 v[50:51], s[12:13], 0, v[50:51]
	v_pk_add_f32 v[36:37], v[184:185], v[36:37]
	global_store_dwordx2 v[50:51], v[48:49], off
	v_mul_f32_e32 v48, v37, v37
	v_mul_f32_e32 v49, v39, v39
	global_store_dwordx4 v[192:193], v[36:39], off offset:512
	v_fmac_f32_e32 v48, v36, v36
	v_fmac_f32_e32 v49, v38, v38
	v_pk_mul_f32 v[38:39], v[6:7], v[38:39]
	v_pk_mul_f32 v[36:37], v[4:5], v[36:37]
	v_pk_add_f32 v[26:27], v[182:183], v[26:27]
	v_cvt_pk_bf16_f32 v36, v36, v37
	v_cvt_pk_bf16_f32 v37, v38, v39
	v_or_b32_e32 v38, 0x100, v58
	v_mov_b32_e32 v39, v59
	v_lshl_add_u64 v[38:39], s[12:13], 0, v[38:39]
	v_pk_add_f32 v[24:25], v[180:181], v[24:25]
	v_add_f32_e32 v56, v56, v57
	global_store_dwordx2 v[38:39], v[36:37], off
	v_mul_f32_e32 v36, v25, v25
	v_mul_f32_e32 v37, v27, v27
	v_add_f32_e32 v56, v65, v56
	v_add_f32_e32 v48, v48, v49
	v_fmac_f32_e32 v36, v24, v24
	v_fmac_f32_e32 v37, v26, v26
	v_add_f32_e32 v48, v56, v48
	v_add_f32_e32 v36, v36, v37
	v_add_f32_e32 v37, v48, v36
	ds_bpermute_b32 v38, v225, v37
	global_store_dwordx4 v[192:193], v[24:27], off offset:576
	v_or_b32_e32 v58, 0x120, v58
	v_readlane_b32 s61, v252, 17
	v_pk_mul_f32 v[24:25], v[0:1], v[24:25]
	v_pk_mul_f32 v[26:27], v[2:3], v[26:27]
	v_cvt_pk_bf16_f32 v36, v24, v25
	s_waitcnt lgkmcnt(0)
	v_add_f32_e32 v24, v37, v38
	ds_bpermute_b32 v25, v224, v24
	v_cvt_pk_bf16_f32 v37, v26, v27
	v_lshl_add_u64 v[26:27], s[12:13], 0, v[58:59]
	v_readlane_b32 s62, v252, 18
	v_readlane_b32 s63, v252, 19
	v_readlane_b32 s64, v252, 20
	v_readlane_b32 s65, v252, 21
	v_readlane_b32 s66, v252, 22
	v_readlane_b32 s67, v252, 23
	v_readlane_b32 s68, v252, 24
	v_readlane_b32 s69, v252, 25
	v_readlane_b32 s70, v252, 26
	v_readlane_b32 s71, v252, 27
	v_readlane_b32 s72, v252, 28
	v_readlane_b32 s73, v252, 29
	global_store_dwordx2 v[26:27], v[36:37], off
	s_and_saveexec_b64 s[24:25], s[4:5]
	s_cbranch_execz .LBB0_236
	v_lshl_add_u64 v[26:27], v[66:67], 2, s[14:15]
	s_waitcnt lgkmcnt(0)
	v_add_f32_e32 v24, v24, v25
	global_atomic_add_f32 v[26:27], v24, off
.LBB0_236:
	s_or_b64 exec, exec, s[24:25]
	v_add_u32_e32 v180, 0x80, v64
	v_ashrrev_i32_e32 v181, 31, v180
	v_readlane_b32 s60, v252, 0
	s_waitcnt lgkmcnt(0)
	v_lshlrev_b64 v[24:25], 13, v[180:181]
	v_readlane_b32 s61, v252, 1
	v_readlane_b32 s62, v252, 2
	v_readlane_b32 s63, v252, 3
	v_lshl_add_u64 v[24:25], s[60:61], 0, v[24:25]
	v_lshl_add_u64 v[24:25], v[140:141], 2, v[24:25]
	global_load_dwordx4 v[64:67], v[24:25], off sc1
	global_load_dwordx4 v[48:51], v[24:25], off offset:64 sc1
	global_load_dwordx4 v[36:39], v[24:25], off offset:512 sc1
	s_nop 0
	global_load_dwordx4 v[24:27], v[24:25], off offset:576 sc1
	v_readlane_b32 s64, v252, 4
	v_readlane_b32 s65, v252, 5
	v_readlane_b32 s66, v252, 6
	v_readlane_b32 s67, v252, 7
	v_readlane_b32 s68, v252, 8
	v_readlane_b32 s69, v252, 9
	v_readlane_b32 s70, v252, 10
	v_readlane_b32 s71, v252, 11
	v_readlane_b32 s72, v252, 12
	v_readlane_b32 s73, v252, 13
	v_readlane_b32 s74, v252, 14
	v_readlane_b32 s75, v252, 15
	v_lshlrev_b64 v[56:57], 11, v[214:215]
	v_readlane_b32 s60, v252, 16
	v_lshl_add_u64 v[56:57], v[56:57], 0, v[140:141]
	v_pk_add_f32 v[46:47], v[178:179], v[46:47]
	v_pk_add_f32 v[44:45], v[176:177], v[44:45]
	v_readlane_b32 s74, v252, 30
	v_readlane_b32 s75, v252, 31
	v_mul_f32_e32 v176, v45, v45
	v_mul_f32_e32 v177, v47, v47
	v_lshl_add_u64 v[58:59], v[56:57], 2, s[74:75]
	global_store_dwordx4 v[58:59], v[44:47], off
	v_fmac_f32_e32 v176, v44, v44
	v_fmac_f32_e32 v177, v46, v46
	v_pk_mul_f32 v[46:47], v[14:15], v[46:47]
	v_pk_mul_f32 v[44:45], v[12:13], v[44:45]
	v_pk_add_f32 v[34:35], v[174:175], v[34:35]
	v_cvt_pk_bf16_f32 v44, v44, v45
	v_cvt_pk_bf16_f32 v45, v46, v47
	v_lshlrev_b64 v[46:47], 1, v[56:57]
	v_lshl_add_u64 v[56:57], s[12:13], 0, v[46:47]
	v_pk_add_f32 v[32:33], v[172:173], v[32:33]
	global_store_dwordx2 v[56:57], v[44:45], off
	v_mul_f32_e32 v44, v33, v33
	v_mul_f32_e32 v45, v35, v35
	global_store_dwordx4 v[58:59], v[32:35], off offset:64
	v_fmac_f32_e32 v44, v32, v32
	v_fmac_f32_e32 v45, v34, v34
	v_pk_mul_f32 v[34:35], v[10:11], v[34:35]
	v_pk_mul_f32 v[32:33], v[8:9], v[32:33]
	v_pk_add_f32 v[22:23], v[170:171], v[22:23]
	v_cvt_pk_bf16_f32 v32, v32, v33
	v_cvt_pk_bf16_f32 v33, v34, v35
	v_or_b32_e32 v34, 32, v46
	v_mov_b32_e32 v35, v47
	v_lshl_add_u64 v[34:35], s[12:13], 0, v[34:35]
	v_pk_add_f32 v[20:21], v[168:169], v[20:21]
	global_store_dwordx2 v[34:35], v[32:33], off
	v_mul_f32_e32 v32, v21, v21
	v_mul_f32_e32 v33, v23, v23
	global_store_dwordx4 v[58:59], v[20:23], off offset:512
	v_fmac_f32_e32 v32, v20, v20
	v_fmac_f32_e32 v33, v22, v22
	v_pk_mul_f32 v[22:23], v[6:7], v[22:23]
	v_pk_mul_f32 v[20:21], v[4:5], v[20:21]
	v_pk_add_f32 v[18:19], v[166:167], v[18:19]
	v_cvt_pk_bf16_f32 v20, v20, v21
	v_cvt_pk_bf16_f32 v21, v22, v23
	v_or_b32_e32 v22, 0x100, v46
	v_mov_b32_e32 v23, v47
	v_lshl_add_u64 v[22:23], s[12:13], 0, v[22:23]
	v_pk_add_f32 v[16:17], v[164:165], v[16:17]
	v_add_f32_e32 v176, v176, v177
	v_add_f32_e32 v44, v44, v45
	global_store_dwordx2 v[22:23], v[20:21], off
	v_mul_f32_e32 v20, v17, v17
	v_mul_f32_e32 v21, v19, v19
	v_add_f32_e32 v44, v176, v44
	v_add_f32_e32 v32, v32, v33
	v_fmac_f32_e32 v20, v16, v16
	v_fmac_f32_e32 v21, v18, v18
	v_add_f32_e32 v32, v44, v32
	v_add_f32_e32 v20, v20, v21
	v_add_f32_e32 v21, v32, v20
	ds_bpermute_b32 v22, v225, v21
	global_store_dwordx4 v[58:59], v[16:19], off offset:576
	v_or_b32_e32 v46, 0x120, v46
	v_readlane_b32 s61, v252, 17
	v_pk_mul_f32 v[16:17], v[0:1], v[16:17]
	v_pk_mul_f32 v[18:19], v[2:3], v[18:19]
	v_cvt_pk_bf16_f32 v20, v16, v17
	s_waitcnt lgkmcnt(0)
	v_add_f32_e32 v16, v21, v22
	ds_bpermute_b32 v17, v224, v16
	v_cvt_pk_bf16_f32 v21, v18, v19
	v_lshl_add_u64 v[18:19], s[12:13], 0, v[46:47]
	v_readlane_b32 s62, v252, 18
	v_readlane_b32 s63, v252, 19
	v_readlane_b32 s64, v252, 20
	v_readlane_b32 s65, v252, 21
	v_readlane_b32 s66, v252, 22
	v_readlane_b32 s67, v252, 23
	v_readlane_b32 s68, v252, 24
	v_readlane_b32 s69, v252, 25
	v_readlane_b32 s70, v252, 26
	v_readlane_b32 s71, v252, 27
	v_readlane_b32 s72, v252, 28
	v_readlane_b32 s73, v252, 29
	global_store_dwordx2 v[18:19], v[20:21], off
	s_and_saveexec_b64 s[24:25], s[4:5]
	s_cbranch_execz .LBB0_238
	v_lshl_add_u64 v[18:19], v[214:215], 2, s[14:15]
	s_waitcnt lgkmcnt(0)
	v_add_f32_e32 v16, v16, v17
	global_atomic_add_f32 v[18:19], v16, off
.LBB0_238:
	s_or_b64 exec, exec, s[24:25]
	s_waitcnt lgkmcnt(0)
	v_lshl_add_u64 v[16:17], v[140:141], 2, v[212:213]
	v_lshl_add_u64 v[18:19], v[16:17], 0, s[20:21]
	v_add_co_u32_e32 v16, vcc, 0x120000, v16
	v_lshlrev_b64 v[20:21], 11, v[196:197]
	s_nop 0
	v_addc_co_u32_e32 v17, vcc, 0, v17, vcc
	global_load_dwordx4 v[44:47], v[18:19], off offset:64 sc1
	global_load_dwordx4 v[32:35], v[18:19], off offset:512 sc1
	global_load_dwordx4 v[56:59], v[16:17], off sc1
	s_nop 0
	global_load_dwordx4 v[16:19], v[18:19], off offset:576 sc1
	v_lshl_add_u64 v[164:165], v[20:21], 0, v[140:141]
	s_waitcnt vmcnt(27)
	v_pk_add_f32 v[22:23], v[160:161], v[62:63]
	v_pk_add_f32 v[20:21], v[158:159], v[60:61]
	v_readlane_b32 s60, v252, 16
	v_readlane_b32 s74, v252, 30
	v_readlane_b32 s75, v252, 31
	v_mul_f32_e32 v62, v21, v21
	v_mul_f32_e32 v63, v23, v23
	v_lshl_add_u64 v[60:61], v[164:165], 2, s[74:75]
	v_fmac_f32_e32 v62, v20, v20
	v_fmac_f32_e32 v63, v22, v22
	global_store_dwordx4 v[60:61], v[20:23], off
	v_add_f32_e32 v158, v62, v63
	v_lshlrev_b64 v[62:63], 1, v[164:165]
	v_pk_mul_f32 v[22:23], v[14:15], v[22:23]
	v_pk_mul_f32 v[20:21], v[12:13], v[20:21]
	v_readlane_b32 s61, v252, 17
	v_cvt_pk_bf16_f32 v20, v20, v21
	v_cvt_pk_bf16_f32 v21, v22, v23
	v_lshl_add_u64 v[22:23], s[12:13], 0, v[62:63]
	global_store_dwordx2 v[22:23], v[20:21], off
	s_waitcnt vmcnt(28)
	v_pk_add_f32 v[22:23], v[156:157], v[54:55]
	v_pk_add_f32 v[20:21], v[154:155], v[52:53]
	v_mul_f32_e32 v53, v23, v23
	v_mul_f32_e32 v52, v21, v21
	global_store_dwordx4 v[60:61], v[20:23], off offset:64
	v_fmac_f32_e32 v52, v20, v20
	v_fmac_f32_e32 v53, v22, v22
	v_pk_mul_f32 v[22:23], v[10:11], v[22:23]
	v_pk_mul_f32 v[20:21], v[8:9], v[20:21]
	v_add_f32_e32 v52, v52, v53
	v_cvt_pk_bf16_f32 v20, v20, v21
	v_cvt_pk_bf16_f32 v21, v22, v23
	v_or_b32_e32 v22, 32, v62
	v_mov_b32_e32 v23, v63
	v_lshl_add_u64 v[22:23], s[12:13], 0, v[22:23]
	global_store_dwordx2 v[22:23], v[20:21], off
	s_waitcnt vmcnt(29)
	v_pk_add_f32 v[22:23], v[152:153], v[42:43]
	v_pk_add_f32 v[20:21], v[150:151], v[40:41]
	v_mul_f32_e32 v41, v23, v23
	v_mul_f32_e32 v40, v21, v21
	global_store_dwordx4 v[60:61], v[20:23], off offset:512
	v_fmac_f32_e32 v40, v20, v20
	v_fmac_f32_e32 v41, v22, v22
	v_pk_mul_f32 v[22:23], v[6:7], v[22:23]
	v_pk_mul_f32 v[20:21], v[4:5], v[20:21]
	v_add_f32_e32 v52, v158, v52
	v_cvt_pk_bf16_f32 v20, v20, v21
	v_cvt_pk_bf16_f32 v21, v22, v23
	v_or_b32_e32 v22, 0x100, v62
	v_mov_b32_e32 v23, v63
	v_lshl_add_u64 v[22:23], s[12:13], 0, v[22:23]
	global_store_dwordx2 v[22:23], v[20:21], off
	s_waitcnt vmcnt(30)
	v_pk_add_f32 v[22:23], v[148:149], v[30:31]
	v_pk_add_f32 v[20:21], v[146:147], v[28:29]
	v_mul_f32_e32 v29, v23, v23
	v_mul_f32_e32 v28, v21, v21
	v_add_f32_e32 v40, v40, v41
	v_fmac_f32_e32 v28, v20, v20
	v_fmac_f32_e32 v29, v22, v22
	v_add_f32_e32 v40, v52, v40
	v_add_f32_e32 v28, v28, v29
	v_add_f32_e32 v29, v40, v28
	ds_bpermute_b32 v30, v225, v29
	global_store_dwordx4 v[60:61], v[20:23], off offset:576
	v_or_b32_e32 v62, 0x120, v62
	v_readlane_b32 s62, v252, 18
	v_pk_mul_f32 v[20:21], v[0:1], v[20:21]
	v_pk_mul_f32 v[22:23], v[2:3], v[22:23]
	v_cvt_pk_bf16_f32 v28, v20, v21
	s_waitcnt lgkmcnt(0)
	v_add_f32_e32 v20, v29, v30
	ds_bpermute_b32 v21, v224, v20
	v_cvt_pk_bf16_f32 v29, v22, v23
	v_lshl_add_u64 v[22:23], s[12:13], 0, v[62:63]
	v_readlane_b32 s63, v252, 19
	v_readlane_b32 s64, v252, 20
	v_readlane_b32 s65, v252, 21
	v_readlane_b32 s66, v252, 22
	v_readlane_b32 s67, v252, 23
	v_readlane_b32 s68, v252, 24
	v_readlane_b32 s69, v252, 25
	v_readlane_b32 s70, v252, 26
	v_readlane_b32 s71, v252, 27
	v_readlane_b32 s72, v252, 28
	v_readlane_b32 s73, v252, 29
	global_store_dwordx2 v[22:23], v[28:29], off
	s_and_saveexec_b64 s[24:25], s[4:5]
	s_cbranch_execz .LBB0_240
	v_lshl_add_u64 v[22:23], v[196:197], 2, s[14:15]
	s_waitcnt lgkmcnt(0)
	v_add_f32_e32 v20, v20, v21
	global_atomic_add_f32 v[22:23], v20, off
.LBB0_240:
	s_or_b64 exec, exec, s[24:25]
	v_or_b32_e32 v146, 32, v180
	v_ashrrev_i32_e32 v147, 31, v146
	v_readlane_b32 s60, v252, 0
	s_waitcnt lgkmcnt(0)
	v_lshlrev_b64 v[20:21], 13, v[146:147]
	v_readlane_b32 s61, v252, 1
	v_readlane_b32 s62, v252, 2
	v_readlane_b32 s63, v252, 3
	v_lshl_add_u64 v[20:21], s[60:61], 0, v[20:21]
	v_lshl_add_u64 v[20:21], v[140:141], 2, v[20:21]
	global_load_dwordx4 v[52:55], v[20:21], off sc1
	global_load_dwordx4 v[40:43], v[20:21], off offset:64 sc1
	global_load_dwordx4 v[28:31], v[20:21], off offset:512 sc1
	s_nop 0
	global_load_dwordx4 v[20:23], v[20:21], off offset:576 sc1
	v_readlane_b32 s64, v252, 4
	v_readlane_b32 s65, v252, 5
	v_readlane_b32 s66, v252, 6
	v_readlane_b32 s67, v252, 7
	v_readlane_b32 s68, v252, 8
	v_readlane_b32 s69, v252, 9
	v_readlane_b32 s70, v252, 10
	v_readlane_b32 s71, v252, 11
	v_readlane_b32 s72, v252, 12
	v_readlane_b32 s73, v252, 13
	v_readlane_b32 s74, v252, 14
	v_readlane_b32 s75, v252, 15
	v_lshlrev_b64 v[60:61], 11, v[180:181]
	v_readlane_b32 s60, v252, 16
	v_lshl_add_u64 v[148:149], v[60:61], 0, v[140:141]
	s_waitcnt vmcnt(27)
	v_pk_add_f32 v[62:63], v[144:145], v[66:67]
	v_pk_add_f32 v[60:61], v[142:143], v[64:65]
	v_readlane_b32 s74, v252, 30
	v_readlane_b32 s75, v252, 31
	v_mul_f32_e32 v66, v61, v61
	v_mul_f32_e32 v67, v63, v63
	v_lshl_add_u64 v[64:65], v[148:149], 2, s[74:75]
	global_store_dwordx4 v[64:65], v[60:63], off
	v_fmac_f32_e32 v66, v60, v60
	v_fmac_f32_e32 v67, v62, v62
	v_pk_mul_f32 v[62:63], v[14:15], v[62:63]
	v_pk_mul_f32 v[60:61], v[12:13], v[60:61]
	v_add_f32_e32 v142, v66, v67
	v_cvt_pk_bf16_f32 v60, v60, v61
	v_cvt_pk_bf16_f32 v61, v62, v63
	v_lshlrev_b64 v[62:63], 1, v[148:149]
	v_lshl_add_u64 v[66:67], s[12:13], 0, v[62:63]
	s_waitcnt vmcnt(27)
	v_pk_add_f32 v[50:51], v[126:127], v[50:51]
	v_pk_add_f32 v[48:49], v[124:125], v[48:49]
	global_store_dwordx2 v[66:67], v[60:61], off
	v_mul_f32_e32 v60, v49, v49
	v_mul_f32_e32 v61, v51, v51
	global_store_dwordx4 v[64:65], v[48:51], off offset:64
	v_fmac_f32_e32 v60, v48, v48
	v_fmac_f32_e32 v61, v50, v50
	v_pk_mul_f32 v[50:51], v[10:11], v[50:51]
	v_pk_mul_f32 v[48:49], v[8:9], v[48:49]
	s_waitcnt vmcnt(28)
	v_pk_add_f32 v[38:39], v[122:123], v[38:39]
	v_cvt_pk_bf16_f32 v48, v48, v49
	v_cvt_pk_bf16_f32 v49, v50, v51
	v_or_b32_e32 v50, 32, v62
	v_mov_b32_e32 v51, v63
	v_lshl_add_u64 v[50:51], s[12:13], 0, v[50:51]
	v_pk_add_f32 v[36:37], v[120:121], v[36:37]
	global_store_dwordx2 v[50:51], v[48:49], off
	v_mul_f32_e32 v48, v37, v37
	v_mul_f32_e32 v49, v39, v39
	global_store_dwordx4 v[64:65], v[36:39], off offset:512
	v_fmac_f32_e32 v48, v36, v36
	v_fmac_f32_e32 v49, v38, v38
	v_pk_mul_f32 v[38:39], v[6:7], v[38:39]
	v_pk_mul_f32 v[36:37], v[4:5], v[36:37]
	s_waitcnt vmcnt(29)
	v_pk_add_f32 v[26:27], v[118:119], v[26:27]
	v_cvt_pk_bf16_f32 v36, v36, v37
	v_cvt_pk_bf16_f32 v37, v38, v39
	v_or_b32_e32 v38, 0x100, v62
	v_mov_b32_e32 v39, v63
	v_lshl_add_u64 v[38:39], s[12:13], 0, v[38:39]
	v_pk_add_f32 v[24:25], v[116:117], v[24:25]
	v_add_f32_e32 v60, v60, v61
	global_store_dwordx2 v[38:39], v[36:37], off
	v_mul_f32_e32 v36, v25, v25
	v_mul_f32_e32 v37, v27, v27
	v_add_f32_e32 v60, v142, v60
	v_add_f32_e32 v48, v48, v49
	v_fmac_f32_e32 v36, v24, v24
	v_fmac_f32_e32 v37, v26, v26
	v_add_f32_e32 v48, v60, v48
	v_add_f32_e32 v36, v36, v37
	v_add_f32_e32 v37, v48, v36
	ds_bpermute_b32 v38, v225, v37
	global_store_dwordx4 v[64:65], v[24:27], off offset:576
	v_or_b32_e32 v62, 0x120, v62
	v_readlane_b32 s61, v252, 17
	v_pk_mul_f32 v[24:25], v[0:1], v[24:25]
	v_pk_mul_f32 v[26:27], v[2:3], v[26:27]
	v_cvt_pk_bf16_f32 v36, v24, v25
	s_waitcnt lgkmcnt(0)
	v_add_f32_e32 v24, v37, v38
	ds_bpermute_b32 v25, v224, v24
	v_cvt_pk_bf16_f32 v37, v26, v27
	v_lshl_add_u64 v[26:27], s[12:13], 0, v[62:63]
	v_readlane_b32 s62, v252, 18
	v_readlane_b32 s63, v252, 19
	v_readlane_b32 s64, v252, 20
	v_readlane_b32 s65, v252, 21
	v_readlane_b32 s66, v252, 22
	v_readlane_b32 s67, v252, 23
	v_readlane_b32 s68, v252, 24
	v_readlane_b32 s69, v252, 25
	v_readlane_b32 s70, v252, 26
	v_readlane_b32 s71, v252, 27
	v_readlane_b32 s72, v252, 28
	v_readlane_b32 s73, v252, 29
	global_store_dwordx2 v[26:27], v[36:37], off
	s_and_saveexec_b64 s[24:25], s[4:5]
	s_cbranch_execz .LBB0_242
	v_lshl_add_u64 v[26:27], v[180:181], 2, s[14:15]
	s_waitcnt lgkmcnt(0)
	v_add_f32_e32 v24, v24, v25
	global_atomic_add_f32 v[26:27], v24, off
.LBB0_242:
	s_or_b64 exec, exec, s[24:25]
	v_or_b32_e32 v64, 48, v180
	v_ashrrev_i32_e32 v65, 31, v64
	v_readlane_b32 s60, v252, 0
	s_waitcnt lgkmcnt(0)
	v_lshlrev_b64 v[24:25], 13, v[64:65]
	v_readlane_b32 s61, v252, 1
	v_or_b32_e32 v66, 16, v180
	v_readlane_b32 s62, v252, 2
	v_lshl_add_u64 v[24:25], s[60:61], 0, v[24:25]
	v_lshl_add_u64 v[24:25], v[140:141], 2, v[24:25]
	global_load_dwordx4 v[60:63], v[24:25], off sc1
	global_load_dwordx4 v[48:51], v[24:25], off offset:64 sc1
	global_load_dwordx4 v[36:39], v[24:25], off offset:512 sc1
	s_nop 0
	global_load_dwordx4 v[24:27], v[24:25], off offset:576 sc1
	v_readlane_b32 s63, v252, 3
	v_readlane_b32 s64, v252, 4
	v_readlane_b32 s65, v252, 5
	v_readlane_b32 s66, v252, 6
	v_readlane_b32 s67, v252, 7
	v_readlane_b32 s68, v252, 8
	v_readlane_b32 s69, v252, 9
	v_readlane_b32 s70, v252, 10
	v_readlane_b32 s71, v252, 11
	v_readlane_b32 s72, v252, 12
	v_readlane_b32 s73, v252, 13
	v_readlane_b32 s74, v252, 14
	v_readlane_b32 s75, v252, 15
	v_ashrrev_i32_e32 v67, 31, v66
	v_lshlrev_b64 v[116:117], 11, v[66:67]
	v_readlane_b32 s60, v252, 16
	v_lshl_add_u64 v[116:117], v[116:117], 0, v[140:141]
	s_waitcnt vmcnt(25)
	v_pk_add_f32 v[58:59], v[114:115], v[58:59]
	v_pk_add_f32 v[56:57], v[112:113], v[56:57]
	v_readlane_b32 s74, v252, 30
	v_readlane_b32 s75, v252, 31
	v_mul_f32_e32 v114, v57, v57
	v_mul_f32_e32 v115, v59, v59
	v_lshl_add_u64 v[112:113], v[116:117], 2, s[74:75]
	global_store_dwordx4 v[112:113], v[56:59], off
	v_fmac_f32_e32 v114, v56, v56
	v_fmac_f32_e32 v115, v58, v58
	v_pk_mul_f32 v[58:59], v[14:15], v[58:59]
	v_pk_mul_f32 v[56:57], v[12:13], v[56:57]
	v_add_f32_e32 v118, v114, v115
	v_cvt_pk_bf16_f32 v56, v56, v57
	v_cvt_pk_bf16_f32 v57, v58, v59
	v_lshlrev_b64 v[58:59], 1, v[116:117]
	v_lshl_add_u64 v[114:115], s[12:13], 0, v[58:59]
	v_pk_add_f32 v[46:47], v[110:111], v[46:47]
	v_pk_add_f32 v[44:45], v[108:109], v[44:45]
	global_store_dwordx2 v[114:115], v[56:57], off
	v_mul_f32_e32 v56, v45, v45
	v_mul_f32_e32 v57, v47, v47
	global_store_dwordx4 v[112:113], v[44:47], off offset:64
	v_fmac_f32_e32 v56, v44, v44
	v_fmac_f32_e32 v57, v46, v46
	v_pk_mul_f32 v[46:47], v[10:11], v[46:47]
	v_pk_mul_f32 v[44:45], v[8:9], v[44:45]
	v_pk_add_f32 v[34:35], v[106:107], v[34:35]
	v_cvt_pk_bf16_f32 v44, v44, v45
	v_cvt_pk_bf16_f32 v45, v46, v47
	v_or_b32_e32 v46, 32, v58
	v_mov_b32_e32 v47, v59
	v_lshl_add_u64 v[46:47], s[12:13], 0, v[46:47]
	v_pk_add_f32 v[32:33], v[104:105], v[32:33]
	global_store_dwordx2 v[46:47], v[44:45], off
	v_mul_f32_e32 v44, v33, v33
	v_mul_f32_e32 v45, v35, v35
	global_store_dwordx4 v[112:113], v[32:35], off offset:512
	v_fmac_f32_e32 v44, v32, v32
	v_fmac_f32_e32 v45, v34, v34
	v_pk_mul_f32 v[34:35], v[6:7], v[34:35]
	v_pk_mul_f32 v[32:33], v[4:5], v[32:33]
	s_waitcnt vmcnt(29)
	v_pk_add_f32 v[18:19], v[102:103], v[18:19]
	v_cvt_pk_bf16_f32 v32, v32, v33
	v_cvt_pk_bf16_f32 v33, v34, v35
	v_or_b32_e32 v34, 0x100, v58
	v_mov_b32_e32 v35, v59
	v_lshl_add_u64 v[34:35], s[12:13], 0, v[34:35]
	v_pk_add_f32 v[16:17], v[100:101], v[16:17]
	v_add_f32_e32 v56, v56, v57
	global_store_dwordx2 v[34:35], v[32:33], off
	v_mul_f32_e32 v32, v17, v17
	v_mul_f32_e32 v33, v19, v19
	v_add_f32_e32 v56, v118, v56
	v_add_f32_e32 v44, v44, v45
	v_fmac_f32_e32 v32, v16, v16
	v_fmac_f32_e32 v33, v18, v18
	v_add_f32_e32 v44, v56, v44
	v_add_f32_e32 v32, v32, v33
	v_add_f32_e32 v33, v44, v32
	ds_bpermute_b32 v34, v225, v33
	global_store_dwordx4 v[112:113], v[16:19], off offset:576
	v_or_b32_e32 v58, 0x120, v58
	v_readlane_b32 s61, v252, 17
	v_pk_mul_f32 v[16:17], v[0:1], v[16:17]
	v_pk_mul_f32 v[18:19], v[2:3], v[18:19]
	v_cvt_pk_bf16_f32 v32, v16, v17
	s_waitcnt lgkmcnt(0)
	v_add_f32_e32 v16, v33, v34
	ds_bpermute_b32 v17, v224, v16
	v_cvt_pk_bf16_f32 v33, v18, v19
	v_lshl_add_u64 v[18:19], s[12:13], 0, v[58:59]
	v_readlane_b32 s62, v252, 18
	v_readlane_b32 s63, v252, 19
	v_readlane_b32 s64, v252, 20
	v_readlane_b32 s65, v252, 21
	v_readlane_b32 s66, v252, 22
	v_readlane_b32 s67, v252, 23
	v_readlane_b32 s68, v252, 24
	v_readlane_b32 s69, v252, 25
	v_readlane_b32 s70, v252, 26
	v_readlane_b32 s71, v252, 27
	v_readlane_b32 s72, v252, 28
	v_readlane_b32 s73, v252, 29
	global_store_dwordx2 v[18:19], v[32:33], off
	s_and_saveexec_b64 s[24:25], s[4:5]
	s_cbranch_execz .LBB0_244
	v_lshl_add_u64 v[18:19], v[66:67], 2, s[14:15]
	s_waitcnt lgkmcnt(0)
	v_add_f32_e32 v16, v16, v17
	global_atomic_add_f32 v[18:19], v16, off

.LBB0_852:
	v_lshl_add_u32 v200, s54, 8, v206
	v_readlane_b32 s60, v252, 16
	v_lshl_or_b32 v188, s55, 8, v208
	v_ashrrev_i32_e32 v201, 31, v200
	v_readlane_b32 s74, v252, 30
	v_readlane_b32 s75, v252, 31
	v_ashrrev_i32_e32 v189, 31, v188
	v_lshlrev_b64 v[112:113], 13, v[200:201]
	v_readlane_b32 s72, v252, 28
	v_readlane_b32 s73, v252, 29
	s_mov_b64 s[82:83], s[74:75]
	v_lshlrev_b64 v[144:145], 2, v[188:189]
	v_readlane_b32 s61, v252, 17
	v_readlane_b32 s62, v252, 18
	v_readlane_b32 s63, v252, 19
	v_readlane_b32 s64, v252, 20
	v_readlane_b32 s65, v252, 21
	v_readlane_b32 s66, v252, 22
	v_readlane_b32 s67, v252, 23
	v_readlane_b32 s68, v252, 24
	v_readlane_b32 s69, v252, 25
	v_readlane_b32 s70, v252, 26
	v_readlane_b32 s71, v252, 27
	v_lshl_add_u64 v[190:191], s[82:83], 0, v[112:113]
	s_mov_b64 s[80:81], s[72:73]
	v_lshl_add_u64 v[230:231], v[190:191], 0, v[144:145]
	v_readlane_b32 s60, v252, 32
	global_load_dwordx4 v[196:199], v[230:231], off sc1
	global_load_dwordx4 v[216:219], v[230:231], off offset:64 sc1
	global_load_dwordx4 v[222:225], v[230:231], off offset:512 sc1
	v_readlane_b32 s74, v252, 46
	v_readlane_b32 s75, v252, 47
	v_or_b32_e32 v202, 16, v200
	v_or_b32_e32 v192, 32, v200
	v_lshl_add_u64 v[112:113], s[74:75], 0, v[144:145]
	global_load_dwordx4 v[128:131], v[112:113], off
	global_load_dwordx4 v[120:123], v[112:113], off offset:64
	global_load_dwordx4 v[116:119], v[112:113], off offset:512
	global_load_dwordx4 v[226:229], v[230:231], off offset:576 sc1
	v_ashrrev_i32_e32 v203, 31, v202
	v_ashrrev_i32_e32 v193, 31, v192
	v_lshlrev_b64 v[146:147], 13, v[202:203]
	v_lshlrev_b64 v[148:149], 13, v[192:193]
	v_lshl_add_u64 v[146:147], s[82:83], 0, v[146:147]
	global_load_dwordx4 v[112:115], v[112:113], off offset:576
	v_lshl_add_u64 v[148:149], s[82:83], 0, v[148:149]
	v_lshl_add_u64 v[204:205], v[146:147], 0, v[144:145]
	v_lshl_add_u64 v[194:195], v[148:149], 0, v[144:145]
	global_load_dwordx4 v[172:175], v[204:205], off sc1
	global_load_dwordx4 v[168:171], v[204:205], off offset:64 sc1
	global_load_dwordx4 v[164:167], v[204:205], off offset:512 sc1
	global_load_dwordx4 v[160:163], v[204:205], off offset:576 sc1
	global_load_dwordx4 v[156:159], v[194:195], off sc1
	global_load_dwordx4 v[152:155], v[194:195], off offset:64 sc1
	global_load_dwordx4 v[148:151], v[194:195], off offset:512 sc1
	global_load_dwordx4 v[144:147], v[194:195], off offset:576 sc1
	v_and_b32_e32 v214, 64, v212
	v_xor_b32_e32 v213, 16, v212
	v_add_u32_e32 v214, 64, v214
	v_xor_b32_e32 v215, 32, v212
	v_cmp_lt_i32_e32 vcc, v213, v214
	v_lshlrev_b64 v[232:233], 11, v[200:201]
	v_lshl_add_u64 v[232:233], v[232:233], 0, v[188:189]
	v_cndmask_b32_e32 v213, v212, v213, vcc
	v_cmp_lt_i32_e32 vcc, v215, v214
	v_lshlrev_b32_e32 v214, 2, v213
	v_lshlrev_b64 v[232:233], 1, v[232:233]
	v_cndmask_b32_e32 v215, v212, v215, vcc
	v_lshlrev_b32_e32 v213, 2, v215
	v_lshl_add_u64 v[234:235], s[14:15], 0, v[232:233]
	v_or_b32_e32 v236, 32, v232
	v_mov_b32_e32 v237, v233
	v_lshl_add_u64 v[236:237], s[14:15], 0, v[236:237]
	v_readlane_b32 s61, v252, 33
	v_readlane_b32 s62, v252, 34
	v_readlane_b32 s63, v252, 35
	v_readlane_b32 s64, v252, 36
	v_readlane_b32 s65, v252, 37
	v_readlane_b32 s66, v252, 38
	v_readlane_b32 s67, v252, 39
	v_readlane_b32 s68, v252, 40
	v_readlane_b32 s69, v252, 41
	v_readlane_b32 s70, v252, 42
	v_readlane_b32 s71, v252, 43
	v_readlane_b32 s72, v252, 44
	v_readlane_b32 s73, v252, 45
	s_waitcnt vmcnt(0)
	v_pk_add_f32 v[138:139], v[138:139], v[198:199]
	v_pk_add_f32 v[136:137], v[136:137], v[196:197]
	v_pk_add_f32 v[142:143], v[142:143], v[218:219]
	v_pk_add_f32 v[140:141], v[140:141], v[216:217]
	v_pk_add_f32 v[134:135], v[134:135], v[224:225]
	v_pk_add_f32 v[132:133], v[132:133], v[222:223]
	v_mul_f32_e32 v215, v137, v137
	v_mul_f32_e32 v221, v139, v139
	v_pk_mul_f32 v[196:197], v[130:131], v[138:139]
	v_pk_mul_f32 v[198:199], v[128:129], v[136:137]
	v_mul_f32_e32 v238, v141, v141
	v_mul_f32_e32 v239, v143, v143
	global_store_dwordx4 v[230:231], v[136:139], off
	v_pk_mul_f32 v[216:217], v[122:123], v[142:143]
	v_pk_mul_f32 v[218:219], v[120:121], v[140:141]
	v_mul_f32_e32 v240, v133, v133
	v_mul_f32_e32 v241, v135, v135
	v_fmac_f32_e32 v215, v136, v136
	v_fmac_f32_e32 v221, v138, v138
	v_cvt_pk_bf16_f32 v136, v198, v199
	v_cvt_pk_bf16_f32 v137, v196, v197
	v_fmac_f32_e32 v238, v140, v140
	v_fmac_f32_e32 v239, v142, v142
	v_cvt_pk_bf16_f32 v138, v218, v219
	v_cvt_pk_bf16_f32 v139, v216, v217
	v_fmac_f32_e32 v240, v132, v132
	v_fmac_f32_e32 v241, v134, v134
	v_add_f32_e32 v197, v215, v221
	global_store_dwordx2 v[234:235], v[136:137], off
	global_store_dwordx4 v[230:231], v[140:143], off offset:64
	v_add_f32_e32 v136, v238, v239
	v_pk_mul_f32 v[224:225], v[116:117], v[132:133]
	global_store_dwordx2 v[236:237], v[138:139], off
	global_store_dwordx4 v[230:231], v[132:135], off offset:512
	v_pk_mul_f32 v[222:223], v[118:119], v[134:135]
	v_cvt_pk_bf16_f32 v196, v224, v225
	v_add_f32_e32 v132, v240, v241
	v_add_f32_e32 v133, v197, v136
	v_add_f32_e32 v134, v133, v132
	v_or_b32_e32 v132, 0x100, v232
	v_mov_b32_e32 v133, v233
	v_cvt_pk_bf16_f32 v197, v222, v223
	v_lshl_add_u64 v[132:133], s[14:15], 0, v[132:133]
	v_pk_add_f32 v[126:127], v[126:127], v[228:229]
	v_pk_add_f32 v[124:125], v[124:125], v[226:227]
	global_store_dwordx2 v[132:133], v[196:197], off
	v_mul_f32_e32 v132, v125, v125
	v_mul_f32_e32 v133, v127, v127
	v_fmac_f32_e32 v132, v124, v124
	v_fmac_f32_e32 v133, v126, v126
	v_add_f32_e32 v132, v132, v133
	v_add_f32_e32 v133, v134, v132
	ds_bpermute_b32 v134, v214, v133
	global_store_dwordx4 v[230:231], v[124:127], off offset:576
	v_or_b32_e32 v232, 0x120, v232
	s_nop 0
	v_pk_mul_f32 v[124:125], v[112:113], v[124:125]
	v_pk_mul_f32 v[126:127], v[114:115], v[126:127]
	v_cvt_pk_bf16_f32 v132, v124, v125
	s_waitcnt lgkmcnt(0)
	v_add_f32_e32 v124, v133, v134
	ds_bpermute_b32 v125, v213, v124
	v_cvt_pk_bf16_f32 v133, v126, v127
	v_lshl_add_u64 v[126:127], s[14:15], 0, v[232:233]
	global_store_dwordx2 v[126:127], v[132:133], off
	s_and_saveexec_b64 s[28:29], s[2:3]
	s_cbranch_execz .LBB0_854
	v_lshl_add_u64 v[126:127], v[200:201], 2, s[16:17]
	s_waitcnt lgkmcnt(0)
	v_add_f32_e32 v124, v124, v125
	global_atomic_add_f32 v[126:127], v124, off
.LBB0_854:
	s_or_b64 exec, exec, s[28:29]
	v_or_b32_e32 v196, 48, v200
	v_ashrrev_i32_e32 v197, 31, v196
	v_readlane_b32 s60, v252, 16
	s_waitcnt lgkmcnt(0)
	v_lshlrev_b64 v[124:125], 13, v[196:197]
	v_readlane_b32 s74, v252, 30
	v_readlane_b32 s75, v252, 31
	v_pk_add_f32 v[110:111], v[110:111], v[174:175]
	v_pk_add_f32 v[108:109], v[108:109], v[172:173]
	v_lshl_add_u64 v[124:125], s[74:75], 0, v[124:125]
	v_lshl_add_u64 v[198:199], v[188:189], 2, v[124:125]
	global_load_dwordx4 v[140:143], v[198:199], off sc1
	global_load_dwordx4 v[136:139], v[198:199], off offset:64 sc1
	global_load_dwordx4 v[132:135], v[198:199], off offset:512 sc1
	global_load_dwordx4 v[124:127], v[198:199], off offset:576 sc1
	v_lshlrev_b64 v[216:217], 11, v[202:203]
	v_mul_f32_e32 v172, v109, v109
	v_mul_f32_e32 v173, v111, v111
	v_lshl_add_u64 v[216:217], v[216:217], 0, v[188:189]
	global_store_dwordx4 v[204:205], v[108:111], off
	v_fmac_f32_e32 v172, v108, v108
	v_fmac_f32_e32 v173, v110, v110
	v_pk_mul_f32 v[110:111], v[130:131], v[110:111]
	v_pk_mul_f32 v[108:109], v[128:129], v[108:109]
	v_add_f32_e32 v174, v172, v173
	v_cvt_pk_bf16_f32 v108, v108, v109
	v_cvt_pk_bf16_f32 v109, v110, v111
	v_lshlrev_b64 v[110:111], 1, v[216:217]
	v_lshl_add_u64 v[172:173], s[14:15], 0, v[110:111]
	v_pk_add_f32 v[106:107], v[106:107], v[170:171]
	v_pk_add_f32 v[104:105], v[104:105], v[168:169]
	global_store_dwordx2 v[172:173], v[108:109], off
	v_mul_f32_e32 v108, v105, v105
	v_mul_f32_e32 v109, v107, v107
	global_store_dwordx4 v[204:205], v[104:107], off offset:64
	v_fmac_f32_e32 v108, v104, v104
	v_fmac_f32_e32 v109, v106, v106
	v_pk_mul_f32 v[106:107], v[122:123], v[106:107]
	v_pk_mul_f32 v[104:105], v[120:121], v[104:105]
	v_pk_add_f32 v[102:103], v[102:103], v[166:167]
	v_cvt_pk_bf16_f32 v104, v104, v105
	v_cvt_pk_bf16_f32 v105, v106, v107
	v_or_b32_e32 v106, 32, v110
	v_mov_b32_e32 v107, v111
	v_lshl_add_u64 v[106:107], s[14:15], 0, v[106:107]
	v_pk_add_f32 v[100:101], v[100:101], v[164:165]
	global_store_dwordx2 v[106:107], v[104:105], off
	v_mul_f32_e32 v104, v101, v101
	v_mul_f32_e32 v105, v103, v103
	global_store_dwordx4 v[204:205], v[100:103], off offset:512
	v_fmac_f32_e32 v104, v100, v100
	v_fmac_f32_e32 v105, v102, v102
	v_pk_mul_f32 v[102:103], v[118:119], v[102:103]
	v_pk_mul_f32 v[100:101], v[116:117], v[100:101]
	v_pk_add_f32 v[98:99], v[98:99], v[162:163]
	v_cvt_pk_bf16_f32 v100, v100, v101
	v_cvt_pk_bf16_f32 v101, v102, v103
	v_or_b32_e32 v102, 0x100, v110
	v_mov_b32_e32 v103, v111
	v_lshl_add_u64 v[102:103], s[14:15], 0, v[102:103]
	v_pk_add_f32 v[96:97], v[96:97], v[160:161]
	v_add_f32_e32 v108, v108, v109
	global_store_dwordx2 v[102:103], v[100:101], off
	v_mul_f32_e32 v100, v97, v97
	v_mul_f32_e32 v101, v99, v99
	v_add_f32_e32 v108, v174, v108
	v_add_f32_e32 v104, v104, v105
	v_fmac_f32_e32 v100, v96, v96
	v_fmac_f32_e32 v101, v98, v98
	v_add_f32_e32 v104, v108, v104
	v_add_f32_e32 v100, v100, v101
	v_add_f32_e32 v101, v104, v100
	ds_bpermute_b32 v102, v214, v101
	global_store_dwordx4 v[204:205], v[96:99], off offset:576
	v_or_b32_e32 v110, 0x120, v110
	v_readlane_b32 s61, v252, 17
	v_pk_mul_f32 v[96:97], v[112:113], v[96:97]
	v_pk_mul_f32 v[98:99], v[114:115], v[98:99]
	v_cvt_pk_bf16_f32 v100, v96, v97
	s_waitcnt lgkmcnt(0)
	v_add_f32_e32 v96, v101, v102
	ds_bpermute_b32 v97, v213, v96
	v_cvt_pk_bf16_f32 v101, v98, v99
	v_lshl_add_u64 v[98:99], s[14:15], 0, v[110:111]
	v_readlane_b32 s62, v252, 18
	v_readlane_b32 s63, v252, 19
	v_readlane_b32 s64, v252, 20
	v_readlane_b32 s65, v252, 21
	v_readlane_b32 s66, v252, 22
	v_readlane_b32 s67, v252, 23
	v_readlane_b32 s68, v252, 24
	v_readlane_b32 s69, v252, 25
	v_readlane_b32 s70, v252, 26
	v_readlane_b32 s71, v252, 27
	v_readlane_b32 s72, v252, 28
	v_readlane_b32 s73, v252, 29
	global_store_dwordx2 v[98:99], v[100:101], off
	s_and_saveexec_b64 s[28:29], s[2:3]
	s_cbranch_execz .LBB0_856
	v_lshl_add_u64 v[98:99], v[202:203], 2, s[16:17]
	s_waitcnt lgkmcnt(0)
	v_add_f32_e32 v96, v96, v97
	global_atomic_add_f32 v[98:99], v96, off
.LBB0_856:
	s_or_b64 exec, exec, s[28:29]
	v_add_u32_e32 v160, 0x80, v200
	v_ashrrev_i32_e32 v161, 31, v160
	v_readlane_b32 s60, v252, 16
	s_waitcnt lgkmcnt(0)
	v_lshlrev_b64 v[96:97], 13, v[160:161]
	v_readlane_b32 s74, v252, 30
	v_readlane_b32 s75, v252, 31
	v_pk_add_f32 v[94:95], v[94:95], v[158:159]
	v_pk_add_f32 v[92:93], v[92:93], v[156:157]
	v_lshl_add_u64 v[96:97], s[74:75], 0, v[96:97]
	v_lshl_add_u64 v[162:163], v[188:189], 2, v[96:97]
	global_load_dwordx4 v[108:111], v[162:163], off sc1
	global_load_dwordx4 v[104:107], v[162:163], off offset:64 sc1
	global_load_dwordx4 v[100:103], v[162:163], off offset:512 sc1
	global_load_dwordx4 v[96:99], v[162:163], off offset:576 sc1
	v_lshlrev_b64 v[164:165], 11, v[192:193]
	v_mul_f32_e32 v156, v93, v93
	v_mul_f32_e32 v157, v95, v95
	v_lshl_add_u64 v[164:165], v[164:165], 0, v[188:189]
	global_store_dwordx4 v[194:195], v[92:95], off
	v_fmac_f32_e32 v156, v92, v92
	v_fmac_f32_e32 v157, v94, v94
	v_pk_mul_f32 v[94:95], v[130:131], v[94:95]
	v_pk_mul_f32 v[92:93], v[128:129], v[92:93]
	v_add_f32_e32 v158, v156, v157
	v_cvt_pk_bf16_f32 v92, v92, v93
	v_cvt_pk_bf16_f32 v93, v94, v95
	v_lshlrev_b64 v[94:95], 1, v[164:165]
	v_lshl_add_u64 v[156:157], s[14:15], 0, v[94:95]
	v_pk_add_f32 v[90:91], v[90:91], v[154:155]
	v_pk_add_f32 v[88:89], v[88:89], v[152:153]
	global_store_dwordx2 v[156:157], v[92:93], off
	v_mul_f32_e32 v92, v89, v89
	v_mul_f32_e32 v93, v91, v91
	global_store_dwordx4 v[194:195], v[88:91], off offset:64
	v_fmac_f32_e32 v92, v88, v88
	v_fmac_f32_e32 v93, v90, v90
	v_pk_mul_f32 v[90:91], v[122:123], v[90:91]
	v_pk_mul_f32 v[88:89], v[120:121], v[88:89]
	v_pk_add_f32 v[86:87], v[86:87], v[150:151]
	v_cvt_pk_bf16_f32 v88, v88, v89
	v_cvt_pk_bf16_f32 v89, v90, v91
	v_or_b32_e32 v90, 32, v94
	v_mov_b32_e32 v91, v95
	v_lshl_add_u64 v[90:91], s[14:15], 0, v[90:91]
	v_pk_add_f32 v[84:85], v[84:85], v[148:149]
	global_store_dwordx2 v[90:91], v[88:89], off
	v_mul_f32_e32 v88, v85, v85
	v_mul_f32_e32 v89, v87, v87
	global_store_dwordx4 v[194:195], v[84:87], off offset:512
	v_fmac_f32_e32 v88, v84, v84
	v_fmac_f32_e32 v89, v86, v86
	v_pk_mul_f32 v[86:87], v[118:119], v[86:87]
	v_pk_mul_f32 v[84:85], v[116:117], v[84:85]
	v_pk_add_f32 v[82:83], v[82:83], v[146:147]
	v_cvt_pk_bf16_f32 v84, v84, v85
	v_cvt_pk_bf16_f32 v85, v86, v87
	v_or_b32_e32 v86, 0x100, v94
	v_mov_b32_e32 v87, v95
	v_lshl_add_u64 v[86:87], s[14:15], 0, v[86:87]
	v_pk_add_f32 v[80:81], v[80:81], v[144:145]
	v_add_f32_e32 v92, v92, v93
	global_store_dwordx2 v[86:87], v[84:85], off
	v_mul_f32_e32 v84, v81, v81
	v_mul_f32_e32 v85, v83, v83
	v_add_f32_e32 v92, v158, v92
	v_add_f32_e32 v88, v88, v89
	v_fmac_f32_e32 v84, v80, v80
	v_fmac_f32_e32 v85, v82, v82
	v_add_f32_e32 v88, v92, v88
	v_add_f32_e32 v84, v84, v85
	v_add_f32_e32 v85, v88, v84
	ds_bpermute_b32 v86, v214, v85
	global_store_dwordx4 v[194:195], v[80:83], off offset:576
	v_or_b32_e32 v94, 0x120, v94
	v_readlane_b32 s61, v252, 17
	v_pk_mul_f32 v[80:81], v[112:113], v[80:81]
	v_pk_mul_f32 v[82:83], v[114:115], v[82:83]
	v_cvt_pk_bf16_f32 v84, v80, v81
	s_waitcnt lgkmcnt(0)
	v_add_f32_e32 v80, v85, v86
	ds_bpermute_b32 v81, v213, v80
	v_cvt_pk_bf16_f32 v85, v82, v83
	v_lshl_add_u64 v[82:83], s[14:15], 0, v[94:95]
	v_readlane_b32 s62, v252, 18
	v_readlane_b32 s63, v252, 19
	v_readlane_b32 s64, v252, 20
	v_readlane_b32 s65, v252, 21
	v_readlane_b32 s66, v252, 22
	v_readlane_b32 s67, v252, 23
	v_readlane_b32 s68, v252, 24
	v_readlane_b32 s69, v252, 25
	v_readlane_b32 s70, v252, 26
	v_readlane_b32 s71, v252, 27
	v_readlane_b32 s72, v252, 28
	v_readlane_b32 s73, v252, 29
	global_store_dwordx2 v[82:83], v[84:85], off
	s_and_saveexec_b64 s[28:29], s[2:3]
	s_cbranch_execz .LBB0_858
	v_lshl_add_u64 v[82:83], v[192:193], 2, s[16:17]
	s_waitcnt lgkmcnt(0)
	v_add_f32_e32 v80, v80, v81
	global_atomic_add_f32 v[82:83], v80, off
.LBB0_858:
	s_or_b64 exec, exec, s[28:29]
	s_waitcnt lgkmcnt(0)
	v_lshl_add_u64 v[80:81], v[188:189], 2, v[190:191]
	v_lshl_add_u64 v[144:145], v[80:81], 0, s[24:25]
	v_add_co_u32_e32 v80, vcc, 0x120000, v80
	s_waitcnt vmcnt(23)
	v_pk_add_f32 v[78:79], v[78:79], v[142:143]
	v_addc_co_u32_e32 v81, vcc, 0, v81, vcc
	global_load_dwordx4 v[88:91], v[144:145], off offset:64 sc1
	global_load_dwordx4 v[84:87], v[144:145], off offset:512 sc1
	global_load_dwordx4 v[92:95], v[80:81], off sc1
	s_nop 0
	global_load_dwordx4 v[80:83], v[144:145], off offset:576 sc1
	v_pk_add_f32 v[76:77], v[76:77], v[140:141]
	v_lshlrev_b64 v[146:147], 11, v[196:197]
	v_mul_f32_e32 v140, v77, v77
	v_mul_f32_e32 v141, v79, v79
	v_lshl_add_u64 v[146:147], v[146:147], 0, v[188:189]
	global_store_dwordx4 v[198:199], v[76:79], off
	v_fmac_f32_e32 v140, v76, v76
	v_fmac_f32_e32 v141, v78, v78
	v_pk_mul_f32 v[78:79], v[130:131], v[78:79]
	v_pk_mul_f32 v[76:77], v[128:129], v[76:77]
	v_add_f32_e32 v142, v140, v141
	v_cvt_pk_bf16_f32 v76, v76, v77
	v_cvt_pk_bf16_f32 v77, v78, v79
	v_lshlrev_b64 v[78:79], 1, v[146:147]
	v_lshl_add_u64 v[140:141], s[14:15], 0, v[78:79]
	s_waitcnt vmcnt(27)
	v_pk_add_f32 v[74:75], v[74:75], v[138:139]
	v_pk_add_f32 v[72:73], v[72:73], v[136:137]
	global_store_dwordx2 v[140:141], v[76:77], off
	v_mul_f32_e32 v76, v73, v73
	v_mul_f32_e32 v77, v75, v75
	global_store_dwordx4 v[198:199], v[72:75], off offset:64
	v_fmac_f32_e32 v76, v72, v72
	v_fmac_f32_e32 v77, v74, v74
	v_pk_mul_f32 v[74:75], v[122:123], v[74:75]
	v_pk_mul_f32 v[72:73], v[120:121], v[72:73]
	s_waitcnt vmcnt(28)
	v_pk_add_f32 v[70:71], v[70:71], v[134:135]
	v_cvt_pk_bf16_f32 v72, v72, v73
	v_cvt_pk_bf16_f32 v73, v74, v75
	v_or_b32_e32 v74, 32, v78
	v_mov_b32_e32 v75, v79
	v_lshl_add_u64 v[74:75], s[14:15], 0, v[74:75]
	v_pk_add_f32 v[68:69], v[68:69], v[132:133]
	global_store_dwordx2 v[74:75], v[72:73], off
	v_mul_f32_e32 v72, v69, v69
	v_mul_f32_e32 v73, v71, v71
	global_store_dwordx4 v[198:199], v[68:71], off offset:512
	v_fmac_f32_e32 v72, v68, v68
	v_fmac_f32_e32 v73, v70, v70
	v_pk_mul_f32 v[70:71], v[118:119], v[70:71]
	v_pk_mul_f32 v[68:69], v[116:117], v[68:69]
	s_waitcnt vmcnt(29)
	v_pk_add_f32 v[66:67], v[66:67], v[126:127]
	v_cvt_pk_bf16_f32 v68, v68, v69
	v_cvt_pk_bf16_f32 v69, v70, v71
	v_or_b32_e32 v70, 0x100, v78
	v_mov_b32_e32 v71, v79
	v_lshl_add_u64 v[70:71], s[14:15], 0, v[70:71]
	v_pk_add_f32 v[64:65], v[64:65], v[124:125]
	v_add_f32_e32 v76, v76, v77
	global_store_dwordx2 v[70:71], v[68:69], off
	v_mul_f32_e32 v68, v65, v65
	v_mul_f32_e32 v69, v67, v67
	v_add_f32_e32 v76, v142, v76
	v_add_f32_e32 v72, v72, v73
	v_fmac_f32_e32 v68, v64, v64
	v_fmac_f32_e32 v69, v66, v66
	v_add_f32_e32 v72, v76, v72
	v_add_f32_e32 v68, v68, v69
	v_add_f32_e32 v69, v72, v68
	ds_bpermute_b32 v70, v214, v69
	global_store_dwordx4 v[198:199], v[64:67], off offset:576
	v_or_b32_e32 v78, 0x120, v78
	s_nop 0
	v_pk_mul_f32 v[64:65], v[112:113], v[64:65]
	v_pk_mul_f32 v[66:67], v[114:115], v[66:67]
	v_cvt_pk_bf16_f32 v68, v64, v65
	s_waitcnt lgkmcnt(0)
	v_add_f32_e32 v64, v69, v70
	ds_bpermute_b32 v65, v213, v64
	v_cvt_pk_bf16_f32 v69, v66, v67
	v_lshl_add_u64 v[66:67], s[14:15], 0, v[78:79]
	global_store_dwordx2 v[66:67], v[68:69], off
	s_and_saveexec_b64 s[28:29], s[2:3]
	s_cbranch_execz .LBB0_860
	v_lshl_add_u64 v[66:67], v[196:197], 2, s[16:17]
	s_waitcnt lgkmcnt(0)
	v_add_f32_e32 v64, v64, v65
	global_atomic_add_f32 v[66:67], v64, off
.LBB0_860:
	s_or_b64 exec, exec, s[28:29]
	v_or_b32_e32 v124, 32, v160
	v_ashrrev_i32_e32 v125, 31, v124
	v_readlane_b32 s60, v252, 16
	s_waitcnt lgkmcnt(0)
	v_lshlrev_b64 v[64:65], 13, v[124:125]
	v_readlane_b32 s74, v252, 30
	v_readlane_b32 s75, v252, 31
	s_waitcnt vmcnt(23)
	v_pk_add_f32 v[62:63], v[62:63], v[110:111]
	v_pk_add_f32 v[60:61], v[60:61], v[108:109]
	v_lshl_add_u64 v[64:65], s[74:75], 0, v[64:65]
	v_lshl_add_u64 v[126:127], v[188:189], 2, v[64:65]
	global_load_dwordx4 v[76:79], v[126:127], off sc1
	global_load_dwordx4 v[72:75], v[126:127], off offset:64 sc1
	global_load_dwordx4 v[68:71], v[126:127], off offset:512 sc1
	global_load_dwordx4 v[64:67], v[126:127], off offset:576 sc1
	v_lshlrev_b64 v[132:133], 11, v[160:161]
	v_mul_f32_e32 v108, v61, v61
	v_mul_f32_e32 v109, v63, v63
	v_lshl_add_u64 v[132:133], v[132:133], 0, v[188:189]
	global_store_dwordx4 v[162:163], v[60:63], off
	v_fmac_f32_e32 v108, v60, v60
	v_fmac_f32_e32 v109, v62, v62
	v_pk_mul_f32 v[62:63], v[130:131], v[62:63]
	v_pk_mul_f32 v[60:61], v[128:129], v[60:61]
	v_add_f32_e32 v110, v108, v109
	v_cvt_pk_bf16_f32 v60, v60, v61
	v_cvt_pk_bf16_f32 v61, v62, v63
	v_lshlrev_b64 v[62:63], 1, v[132:133]
	v_lshl_add_u64 v[108:109], s[14:15], 0, v[62:63]
	s_waitcnt vmcnt(27)
	v_pk_add_f32 v[58:59], v[58:59], v[106:107]
	v_pk_add_f32 v[56:57], v[56:57], v[104:105]
	global_store_dwordx2 v[108:109], v[60:61], off
	v_mul_f32_e32 v60, v57, v57
	v_mul_f32_e32 v61, v59, v59
	global_store_dwordx4 v[162:163], v[56:59], off offset:64
	v_fmac_f32_e32 v60, v56, v56
	v_fmac_f32_e32 v61, v58, v58
	v_pk_mul_f32 v[58:59], v[122:123], v[58:59]
	v_pk_mul_f32 v[56:57], v[120:121], v[56:57]
	s_waitcnt vmcnt(28)
	v_pk_add_f32 v[54:55], v[54:55], v[102:103]
	v_cvt_pk_bf16_f32 v56, v56, v57
	v_cvt_pk_bf16_f32 v57, v58, v59
	v_or_b32_e32 v58, 32, v62
	v_mov_b32_e32 v59, v63
	v_lshl_add_u64 v[58:59], s[14:15], 0, v[58:59]
	v_pk_add_f32 v[52:53], v[52:53], v[100:101]
	global_store_dwordx2 v[58:59], v[56:57], off
	v_mul_f32_e32 v56, v53, v53
	v_mul_f32_e32 v57, v55, v55
	global_store_dwordx4 v[162:163], v[52:55], off offset:512
	v_fmac_f32_e32 v56, v52, v52
	v_fmac_f32_e32 v57, v54, v54
	v_pk_mul_f32 v[54:55], v[118:119], v[54:55]
	v_pk_mul_f32 v[52:53], v[116:117], v[52:53]
	s_waitcnt vmcnt(29)
	v_pk_add_f32 v[50:51], v[50:51], v[98:99]
	v_cvt_pk_bf16_f32 v52, v52, v53
	v_cvt_pk_bf16_f32 v53, v54, v55
	v_or_b32_e32 v54, 0x100, v62
	v_mov_b32_e32 v55, v63
	v_lshl_add_u64 v[54:55], s[14:15], 0, v[54:55]
	v_pk_add_f32 v[48:49], v[48:49], v[96:97]
	v_add_f32_e32 v60, v60, v61
	global_store_dwordx2 v[54:55], v[52:53], off
	v_mul_f32_e32 v52, v49, v49
	v_mul_f32_e32 v53, v51, v51
	v_add_f32_e32 v60, v110, v60
	v_add_f32_e32 v56, v56, v57
	v_fmac_f32_e32 v52, v48, v48
	v_fmac_f32_e32 v53, v50, v50
	v_add_f32_e32 v56, v60, v56
	v_add_f32_e32 v52, v52, v53
	v_add_f32_e32 v53, v56, v52
	ds_bpermute_b32 v54, v214, v53
	global_store_dwordx4 v[162:163], v[48:51], off offset:576
	v_or_b32_e32 v62, 0x120, v62
	v_readlane_b32 s61, v252, 17
	v_pk_mul_f32 v[48:49], v[112:113], v[48:49]
	v_pk_mul_f32 v[50:51], v[114:115], v[50:51]
	v_cvt_pk_bf16_f32 v52, v48, v49
	s_waitcnt lgkmcnt(0)
	v_add_f32_e32 v48, v53, v54
	ds_bpermute_b32 v49, v213, v48
	v_cvt_pk_bf16_f32 v53, v50, v51
	v_lshl_add_u64 v[50:51], s[14:15], 0, v[62:63]
	v_readlane_b32 s62, v252, 18
	v_readlane_b32 s63, v252, 19
	v_readlane_b32 s64, v252, 20
	v_readlane_b32 s65, v252, 21
	v_readlane_b32 s66, v252, 22
	v_readlane_b32 s67, v252, 23
	v_readlane_b32 s68, v252, 24
	v_readlane_b32 s69, v252, 25
	v_readlane_b32 s70, v252, 26
	v_readlane_b32 s71, v252, 27
	v_readlane_b32 s72, v252, 28
	v_readlane_b32 s73, v252, 29
	global_store_dwordx2 v[50:51], v[52:53], off
	s_and_saveexec_b64 s[28:29], s[2:3]
	s_cbranch_execz .LBB0_862
	v_lshl_add_u64 v[50:51], v[160:161], 2, s[16:17]
	s_waitcnt lgkmcnt(0)
	v_add_f32_e32 v48, v48, v49
	global_atomic_add_f32 v[50:51], v48, off
.LBB0_862:
	s_or_b64 exec, exec, s[28:29]
	v_or_b32_e32 v96, 48, v160
	v_ashrrev_i32_e32 v97, 31, v96
	v_readlane_b32 s60, v252, 16
	s_waitcnt lgkmcnt(0)
	v_lshlrev_b64 v[48:49], 13, v[96:97]
	v_readlane_b32 s74, v252, 30
	v_readlane_b32 s75, v252, 31
	v_or_b32_e32 v100, 16, v160
	v_ashrrev_i32_e32 v101, 31, v100
	v_lshl_add_u64 v[48:49], s[74:75], 0, v[48:49]
	v_lshl_add_u64 v[98:99], v[188:189], 2, v[48:49]
	global_load_dwordx4 v[60:63], v[98:99], off sc1
	global_load_dwordx4 v[56:59], v[98:99], off offset:64 sc1
	global_load_dwordx4 v[52:55], v[98:99], off offset:512 sc1
	global_load_dwordx4 v[48:51], v[98:99], off offset:576 sc1
	s_waitcnt vmcnt(25)
	v_pk_add_f32 v[46:47], v[46:47], v[94:95]
	v_pk_add_f32 v[44:45], v[44:45], v[92:93]
	v_lshlrev_b64 v[102:103], 11, v[100:101]
	v_mul_f32_e32 v92, v45, v45
	v_mul_f32_e32 v93, v47, v47
	v_lshl_add_u64 v[102:103], v[102:103], 0, v[188:189]
	global_store_dwordx4 v[144:145], v[44:47], off
	v_fmac_f32_e32 v92, v44, v44
	v_fmac_f32_e32 v93, v46, v46
	v_pk_mul_f32 v[46:47], v[130:131], v[46:47]
	v_pk_mul_f32 v[44:45], v[128:129], v[44:45]
	v_add_f32_e32 v94, v92, v93
	v_cvt_pk_bf16_f32 v44, v44, v45
	v_cvt_pk_bf16_f32 v45, v46, v47
	v_lshlrev_b64 v[46:47], 1, v[102:103]
	v_lshl_add_u64 v[92:93], s[14:15], 0, v[46:47]
	v_pk_add_f32 v[42:43], v[42:43], v[90:91]
	v_pk_add_f32 v[40:41], v[40:41], v[88:89]
	global_store_dwordx2 v[92:93], v[44:45], off
	v_mul_f32_e32 v44, v41, v41
	v_mul_f32_e32 v45, v43, v43
	global_store_dwordx4 v[144:145], v[40:43], off offset:64
	v_fmac_f32_e32 v44, v40, v40
	v_fmac_f32_e32 v45, v42, v42
	v_pk_mul_f32 v[42:43], v[122:123], v[42:43]
	v_pk_mul_f32 v[40:41], v[120:121], v[40:41]
	v_pk_add_f32 v[38:39], v[38:39], v[86:87]
	v_cvt_pk_bf16_f32 v40, v40, v41
	v_cvt_pk_bf16_f32 v41, v42, v43
	v_or_b32_e32 v42, 32, v46
	v_mov_b32_e32 v43, v47
	v_lshl_add_u64 v[42:43], s[14:15], 0, v[42:43]
	v_pk_add_f32 v[36:37], v[36:37], v[84:85]
	global_store_dwordx2 v[42:43], v[40:41], off
	v_mul_f32_e32 v40, v37, v37
	v_mul_f32_e32 v41, v39, v39
	global_store_dwordx4 v[144:145], v[36:39], off offset:512
	v_fmac_f32_e32 v40, v36, v36
	v_fmac_f32_e32 v41, v38, v38
	v_pk_mul_f32 v[38:39], v[118:119], v[38:39]
	v_pk_mul_f32 v[36:37], v[116:117], v[36:37]
	s_waitcnt vmcnt(29)
	v_pk_add_f32 v[34:35], v[34:35], v[82:83]
	v_cvt_pk_bf16_f32 v36, v36, v37
	v_cvt_pk_bf16_f32 v37, v38, v39
	v_or_b32_e32 v38, 0x100, v46
	v_mov_b32_e32 v39, v47
	v_lshl_add_u64 v[38:39], s[14:15], 0, v[38:39]
	v_pk_add_f32 v[32:33], v[32:33], v[80:81]
	v_add_f32_e32 v44, v44, v45
	global_store_dwordx2 v[38:39], v[36:37], off
	v_mul_f32_e32 v36, v33, v33
	v_mul_f32_e32 v37, v35, v35
	v_add_f32_e32 v44, v94, v44
	v_add_f32_e32 v40, v40, v41
	v_fmac_f32_e32 v36, v32, v32
	v_fmac_f32_e32 v37, v34, v34
	v_add_f32_e32 v40, v44, v40
	v_add_f32_e32 v36, v36, v37
	v_add_f32_e32 v37, v40, v36
	ds_bpermute_b32 v38, v214, v37
	global_store_dwordx4 v[144:145], v[32:35], off offset:576
	v_or_b32_e32 v46, 0x120, v46
	v_readlane_b32 s61, v252, 17
	v_pk_mul_f32 v[32:33], v[112:113], v[32:33]
	v_pk_mul_f32 v[34:35], v[114:115], v[34:35]
	v_cvt_pk_bf16_f32 v36, v32, v33
	s_waitcnt lgkmcnt(0)
	v_add_f32_e32 v32, v37, v38
	ds_bpermute_b32 v33, v213, v32
	v_cvt_pk_bf16_f32 v37, v34, v35
	v_lshl_add_u64 v[34:35], s[14:15], 0, v[46:47]
	v_readlane_b32 s62, v252, 18
	v_readlane_b32 s63, v252, 19
	v_readlane_b32 s64, v252, 20
	v_readlane_b32 s65, v252, 21
	v_readlane_b32 s66, v252, 22
	v_readlane_b32 s67, v252, 23
	v_readlane_b32 s68, v252, 24
	v_readlane_b32 s69, v252, 25
	v_readlane_b32 s70, v252, 26
	v_readlane_b32 s71, v252, 27
	v_readlane_b32 s72, v252, 28
	v_readlane_b32 s73, v252, 29
	global_store_dwordx2 v[34:35], v[36:37], off
	s_and_saveexec_b64 s[28:29], s[2:3]
	s_cbranch_execz .LBB0_864
	v_lshl_add_u64 v[34:35], v[100:101], 2, s[16:17]
	s_waitcnt lgkmcnt(0)
	v_add_f32_e32 v32, v32, v33
	global_atomic_add_f32 v[34:35], v32, off

.LBB0_1060:
	v_readlane_b32 s60, v252, 16
	v_lshl_add_u32 v64, s54, 8, v218
	v_readlane_b32 s61, v252, 17
	v_readlane_b32 s62, v252, 18
	v_readlane_b32 s63, v252, 19
	v_readlane_b32 s72, v252, 28
	v_readlane_b32 s73, v252, 29
	v_lshl_or_b32 v144, s55, 8, v221
	v_ashrrev_i32_e32 v65, 31, v64
	v_readlane_b32 s74, v252, 30
	v_readlane_b32 s75, v252, 31
	s_mov_b64 s[60:61], s[72:73]
	v_ashrrev_i32_e32 v145, 31, v144
	s_waitcnt lgkmcnt(0)
	v_lshlrev_b64 v[0:1], 13, v[64:65]
	s_mov_b64 s[62:63], s[74:75]
	v_lshlrev_b64 v[16:17], 2, v[144:145]
	v_lshl_add_u64 v[210:211], s[62:63], 0, v[0:1]
	v_readlane_b32 s66, v252, 22
	v_readlane_b32 s67, v252, 23
	v_lshl_add_u64 v[228:229], v[210:211], 0, v[16:17]
	s_mov_b64 s[54:55], s[66:67]
	global_load_dwordx4 v[28:31], v[228:229], off sc1
	global_load_dwordx4 v[40:43], v[228:229], off offset:64 sc1
	global_load_dwordx4 v[52:55], v[228:229], off offset:512 sc1
	v_lshl_add_u64 v[0:1], s[54:55], 0, v[16:17]
	global_load_dwordx4 v[12:15], v[0:1], off
	global_load_dwordx4 v[8:11], v[0:1], off offset:64
	global_load_dwordx4 v[4:7], v[0:1], off offset:512
	global_load_dwordx4 v[60:63], v[228:229], off offset:576 sc1
	v_or_b32_e32 v66, 16, v64
	v_or_b32_e32 v212, 32, v64
	v_ashrrev_i32_e32 v67, 31, v66
	v_ashrrev_i32_e32 v213, 31, v212
	v_lshlrev_b64 v[18:19], 13, v[66:67]
	v_lshlrev_b64 v[20:21], 13, v[212:213]
	v_lshl_add_u64 v[18:19], s[62:63], 0, v[18:19]
	global_load_dwordx4 v[0:3], v[0:1], off offset:576
	v_lshl_add_u64 v[20:21], s[62:63], 0, v[20:21]
	v_lshl_add_u64 v[216:217], v[18:19], 0, v[16:17]
	v_lshl_add_u64 v[214:215], v[20:21], 0, v[16:17]
	global_load_dwordx4 v[56:59], v[216:217], off sc1
	global_load_dwordx4 v[48:51], v[216:217], off offset:64 sc1
	global_load_dwordx4 v[36:39], v[216:217], off offset:512 sc1
	global_load_dwordx4 v[24:27], v[216:217], off offset:576 sc1
	global_load_dwordx4 v[44:47], v[214:215], off sc1
	global_load_dwordx4 v[32:35], v[214:215], off offset:64 sc1
	global_load_dwordx4 v[20:23], v[214:215], off offset:512 sc1
	global_load_dwordx4 v[16:19], v[214:215], off offset:576 sc1
	v_and_b32_e32 v227, 64, v225
	v_xor_b32_e32 v226, 16, v225
	v_add_u32_e32 v227, 64, v227
	v_xor_b32_e32 v230, 32, v225
	v_cmp_lt_i32_e32 vcc, v226, v227
	v_readlane_b32 s64, v252, 20
	v_readlane_b32 s65, v252, 21
	v_cndmask_b32_e32 v226, v225, v226, vcc
	v_cmp_lt_i32_e32 vcc, v230, v227
	v_lshlrev_b32_e32 v227, 2, v226
	v_readlane_b32 s68, v252, 24
	v_cndmask_b32_e32 v232, v225, v230, vcc
	v_lshlrev_b64 v[230:231], 11, v[64:65]
	v_lshl_add_u64 v[230:231], v[230:231], 0, v[144:145]
	v_lshlrev_b64 v[230:231], 1, v[230:231]
	v_lshlrev_b32_e32 v226, 2, v232
	v_lshl_add_u64 v[232:233], s[12:13], 0, v[230:231]
	v_or_b32_e32 v234, 32, v230
	v_mov_b32_e32 v235, v231
	v_lshl_add_u64 v[234:235], s[12:13], 0, v[234:235]
	v_readlane_b32 s69, v252, 25
	v_readlane_b32 s70, v252, 26
	v_readlane_b32 s71, v252, 27
	s_waitcnt vmcnt(0)
	v_pk_add_f32 v[30:31], v[198:199], v[30:31]
	v_pk_add_f32 v[28:29], v[200:201], v[28:29]
	v_pk_add_f32 v[42:43], v[202:203], v[42:43]
	v_pk_add_f32 v[40:41], v[204:205], v[40:41]
	v_pk_add_f32 v[54:55], v[208:209], v[54:55]
	v_pk_add_f32 v[52:53], v[206:207], v[52:53]
	v_mul_f32_e32 v236, v29, v29
	v_mul_f32_e32 v237, v31, v31
	v_pk_mul_f32 v[198:199], v[14:15], v[30:31]
	v_pk_mul_f32 v[200:201], v[12:13], v[28:29]
	v_mul_f32_e32 v238, v41, v41
	v_mul_f32_e32 v239, v43, v43
	global_store_dwordx4 v[228:229], v[28:31], off
	v_mul_f32_e32 v240, v53, v53
	v_mul_f32_e32 v241, v55, v55
	v_fmac_f32_e32 v236, v28, v28
	v_fmac_f32_e32 v237, v30, v30
	v_cvt_pk_bf16_f32 v28, v200, v201
	v_cvt_pk_bf16_f32 v29, v198, v199
	v_fmac_f32_e32 v238, v40, v40
	v_fmac_f32_e32 v239, v42, v42
	v_fmac_f32_e32 v240, v52, v52
	v_fmac_f32_e32 v241, v54, v54
	v_add_f32_e32 v199, v236, v237
	global_store_dwordx2 v[232:233], v[28:29], off
	global_store_dwordx4 v[228:229], v[40:43], off offset:64
	v_add_f32_e32 v28, v238, v239
	v_add_f32_e32 v29, v240, v241
	v_add_f32_e32 v28, v199, v28
	v_pk_mul_f32 v[202:203], v[10:11], v[42:43]
	v_pk_mul_f32 v[204:205], v[8:9], v[40:41]
	v_pk_mul_f32 v[206:207], v[6:7], v[54:55]
	v_pk_mul_f32 v[208:209], v[4:5], v[52:53]
	v_add_f32_e32 v40, v28, v29
	v_or_b32_e32 v28, 0x100, v230
	v_mov_b32_e32 v29, v231
	v_cvt_pk_bf16_f32 v30, v204, v205
	v_cvt_pk_bf16_f32 v31, v202, v203
	v_cvt_pk_bf16_f32 v198, v208, v209
	v_cvt_pk_bf16_f32 v199, v206, v207
	v_lshl_add_u64 v[28:29], s[12:13], 0, v[28:29]
	global_store_dwordx2 v[234:235], v[30:31], off
	global_store_dwordx4 v[228:229], v[52:55], off offset:512
	global_store_dwordx2 v[28:29], v[198:199], off
	v_pk_add_f32 v[30:31], v[196:197], v[62:63]
	v_pk_add_f32 v[28:29], v[194:195], v[60:61]
	v_mul_f32_e32 v42, v31, v31
	v_mul_f32_e32 v41, v29, v29
	v_fmac_f32_e32 v41, v28, v28
	v_fmac_f32_e32 v42, v30, v30
	v_add_f32_e32 v41, v41, v42
	v_add_f32_e32 v41, v40, v41
	ds_bpermute_b32 v42, v227, v41
	global_store_dwordx4 v[228:229], v[28:31], off offset:576
	v_or_b32_e32 v230, 0x120, v230
	s_nop 0
	v_pk_mul_f32 v[28:29], v[0:1], v[28:29]
	v_pk_mul_f32 v[30:31], v[2:3], v[30:31]
	v_cvt_pk_bf16_f32 v40, v28, v29
	s_waitcnt lgkmcnt(0)
	v_add_f32_e32 v28, v41, v42
	ds_bpermute_b32 v29, v226, v28
	v_cvt_pk_bf16_f32 v41, v30, v31
	v_lshl_add_u64 v[30:31], s[12:13], 0, v[230:231]
	global_store_dwordx2 v[30:31], v[40:41], off
	s_and_saveexec_b64 s[24:25], s[2:3]
	s_cbranch_execz .LBB0_1062
	v_lshl_add_u64 v[30:31], v[64:65], 2, s[14:15]
	s_waitcnt lgkmcnt(0)
	v_add_f32_e32 v28, v28, v29
	global_atomic_add_f32 v[30:31], v28, off
.LBB0_1062:
	s_or_b64 exec, exec, s[24:25]
	v_or_b32_e32 v194, 48, v64
	v_ashrrev_i32_e32 v195, 31, v194
	v_readlane_b32 s60, v252, 16
	s_waitcnt lgkmcnt(0)
	v_lshlrev_b64 v[28:29], 13, v[194:195]
	v_readlane_b32 s74, v252, 30
	v_readlane_b32 s75, v252, 31
	v_pk_add_f32 v[58:59], v[192:193], v[58:59]
	v_pk_add_f32 v[56:57], v[190:191], v[56:57]
	v_lshl_add_u64 v[28:29], s[74:75], 0, v[28:29]
	v_lshl_add_u64 v[196:197], v[144:145], 2, v[28:29]
	global_load_dwordx4 v[60:63], v[196:197], off sc1
	global_load_dwordx4 v[52:55], v[196:197], off offset:64 sc1
	global_load_dwordx4 v[40:43], v[196:197], off offset:512 sc1
	global_load_dwordx4 v[28:31], v[196:197], off offset:576 sc1
	v_lshlrev_b64 v[198:199], 11, v[66:67]
	v_mul_f32_e32 v65, v57, v57
	v_mul_f32_e32 v190, v59, v59
	v_lshl_add_u64 v[198:199], v[198:199], 0, v[144:145]
	global_store_dwordx4 v[216:217], v[56:59], off
	v_fmac_f32_e32 v65, v56, v56
	v_fmac_f32_e32 v190, v58, v58
	v_pk_mul_f32 v[58:59], v[14:15], v[58:59]
	v_pk_mul_f32 v[56:57], v[12:13], v[56:57]
	v_add_f32_e32 v65, v65, v190
	v_cvt_pk_bf16_f32 v56, v56, v57
	v_cvt_pk_bf16_f32 v57, v58, v59
	v_lshlrev_b64 v[58:59], 1, v[198:199]
	v_lshl_add_u64 v[190:191], s[12:13], 0, v[58:59]
	v_pk_add_f32 v[50:51], v[188:189], v[50:51]
	v_pk_add_f32 v[48:49], v[186:187], v[48:49]
	global_store_dwordx2 v[190:191], v[56:57], off
	v_mul_f32_e32 v56, v49, v49
	v_mul_f32_e32 v57, v51, v51
	global_store_dwordx4 v[216:217], v[48:51], off offset:64
	v_fmac_f32_e32 v56, v48, v48
	v_fmac_f32_e32 v57, v50, v50
	v_pk_mul_f32 v[50:51], v[10:11], v[50:51]
	v_pk_mul_f32 v[48:49], v[8:9], v[48:49]
	v_pk_add_f32 v[38:39], v[184:185], v[38:39]
	v_cvt_pk_bf16_f32 v48, v48, v49
	v_cvt_pk_bf16_f32 v49, v50, v51
	v_or_b32_e32 v50, 32, v58
	v_mov_b32_e32 v51, v59
	v_lshl_add_u64 v[50:51], s[12:13], 0, v[50:51]
	v_pk_add_f32 v[36:37], v[182:183], v[36:37]
	global_store_dwordx2 v[50:51], v[48:49], off
	v_mul_f32_e32 v48, v37, v37
	v_mul_f32_e32 v49, v39, v39
	global_store_dwordx4 v[216:217], v[36:39], off offset:512
	v_fmac_f32_e32 v48, v36, v36
	v_fmac_f32_e32 v49, v38, v38
	v_pk_mul_f32 v[38:39], v[6:7], v[38:39]
	v_pk_mul_f32 v[36:37], v[4:5], v[36:37]
	v_pk_add_f32 v[26:27], v[180:181], v[26:27]
	v_cvt_pk_bf16_f32 v36, v36, v37
	v_cvt_pk_bf16_f32 v37, v38, v39
	v_or_b32_e32 v38, 0x100, v58
	v_mov_b32_e32 v39, v59
	v_lshl_add_u64 v[38:39], s[12:13], 0, v[38:39]
	v_pk_add_f32 v[24:25], v[178:179], v[24:25]
	v_add_f32_e32 v56, v56, v57
	global_store_dwordx2 v[38:39], v[36:37], off
	v_mul_f32_e32 v36, v25, v25
	v_mul_f32_e32 v37, v27, v27
	v_add_f32_e32 v56, v65, v56
	v_add_f32_e32 v48, v48, v49
	v_fmac_f32_e32 v36, v24, v24
	v_fmac_f32_e32 v37, v26, v26
	v_add_f32_e32 v48, v56, v48
	v_add_f32_e32 v36, v36, v37
	v_add_f32_e32 v37, v48, v36
	ds_bpermute_b32 v38, v227, v37
	global_store_dwordx4 v[216:217], v[24:27], off offset:576
	v_or_b32_e32 v58, 0x120, v58
	v_readlane_b32 s61, v252, 17
	v_pk_mul_f32 v[24:25], v[0:1], v[24:25]
	v_pk_mul_f32 v[26:27], v[2:3], v[26:27]
	v_cvt_pk_bf16_f32 v36, v24, v25
	s_waitcnt lgkmcnt(0)
	v_add_f32_e32 v24, v37, v38
	ds_bpermute_b32 v25, v226, v24
	v_cvt_pk_bf16_f32 v37, v26, v27
	v_lshl_add_u64 v[26:27], s[12:13], 0, v[58:59]
	v_readlane_b32 s62, v252, 18
	v_readlane_b32 s63, v252, 19
	v_readlane_b32 s64, v252, 20
	v_readlane_b32 s65, v252, 21
	v_readlane_b32 s66, v252, 22
	v_readlane_b32 s67, v252, 23
	v_readlane_b32 s68, v252, 24
	v_readlane_b32 s69, v252, 25
	v_readlane_b32 s70, v252, 26
	v_readlane_b32 s71, v252, 27
	v_readlane_b32 s72, v252, 28
	v_readlane_b32 s73, v252, 29
	global_store_dwordx2 v[26:27], v[36:37], off
	s_and_saveexec_b64 s[24:25], s[2:3]
	s_cbranch_execz .LBB0_1064
	v_lshl_add_u64 v[26:27], v[66:67], 2, s[14:15]
	s_waitcnt lgkmcnt(0)
	v_add_f32_e32 v24, v24, v25
	global_atomic_add_f32 v[26:27], v24, off
.LBB0_1064:
	s_or_b64 exec, exec, s[24:25]
	v_add_u32_e32 v178, 0x80, v64
	v_ashrrev_i32_e32 v179, 31, v178
	v_readlane_b32 s60, v252, 16
	s_waitcnt lgkmcnt(0)
	v_lshlrev_b64 v[24:25], 13, v[178:179]
	v_readlane_b32 s74, v252, 30
	v_readlane_b32 s75, v252, 31
	v_pk_add_f32 v[46:47], v[176:177], v[46:47]
	v_pk_add_f32 v[44:45], v[174:175], v[44:45]
	v_lshl_add_u64 v[24:25], s[74:75], 0, v[24:25]
	v_lshl_add_u64 v[180:181], v[144:145], 2, v[24:25]
	global_load_dwordx4 v[64:67], v[180:181], off sc1
	global_load_dwordx4 v[48:51], v[180:181], off offset:64 sc1
	global_load_dwordx4 v[36:39], v[180:181], off offset:512 sc1
	global_load_dwordx4 v[24:27], v[180:181], off offset:576 sc1
	v_lshlrev_b64 v[56:57], 11, v[212:213]
	v_mul_f32_e32 v58, v45, v45
	v_mul_f32_e32 v59, v47, v47
	v_lshl_add_u64 v[56:57], v[56:57], 0, v[144:145]
	global_store_dwordx4 v[214:215], v[44:47], off
	v_fmac_f32_e32 v58, v44, v44
	v_fmac_f32_e32 v59, v46, v46
	v_pk_mul_f32 v[46:47], v[14:15], v[46:47]
	v_pk_mul_f32 v[44:45], v[12:13], v[44:45]
	v_pk_add_f32 v[34:35], v[172:173], v[34:35]
	v_cvt_pk_bf16_f32 v44, v44, v45
	v_cvt_pk_bf16_f32 v45, v46, v47
	v_lshlrev_b64 v[46:47], 1, v[56:57]
	v_lshl_add_u64 v[56:57], s[12:13], 0, v[46:47]
	v_pk_add_f32 v[32:33], v[170:171], v[32:33]
	global_store_dwordx2 v[56:57], v[44:45], off
	v_mul_f32_e32 v44, v33, v33
	v_mul_f32_e32 v45, v35, v35
	global_store_dwordx4 v[214:215], v[32:35], off offset:64
	v_fmac_f32_e32 v44, v32, v32
	v_fmac_f32_e32 v45, v34, v34
	v_pk_mul_f32 v[34:35], v[10:11], v[34:35]
	v_pk_mul_f32 v[32:33], v[8:9], v[32:33]
	v_pk_add_f32 v[22:23], v[168:169], v[22:23]
	v_cvt_pk_bf16_f32 v32, v32, v33
	v_cvt_pk_bf16_f32 v33, v34, v35
	v_or_b32_e32 v34, 32, v46
	v_mov_b32_e32 v35, v47
	v_lshl_add_u64 v[34:35], s[12:13], 0, v[34:35]
	v_pk_add_f32 v[20:21], v[166:167], v[20:21]
	global_store_dwordx2 v[34:35], v[32:33], off
	v_mul_f32_e32 v32, v21, v21
	v_mul_f32_e32 v33, v23, v23
	global_store_dwordx4 v[214:215], v[20:23], off offset:512
	v_fmac_f32_e32 v32, v20, v20
	v_fmac_f32_e32 v33, v22, v22
	v_pk_mul_f32 v[22:23], v[6:7], v[22:23]
	v_pk_mul_f32 v[20:21], v[4:5], v[20:21]
	v_pk_add_f32 v[18:19], v[164:165], v[18:19]
	v_cvt_pk_bf16_f32 v20, v20, v21
	v_cvt_pk_bf16_f32 v21, v22, v23
	v_or_b32_e32 v22, 0x100, v46
	v_mov_b32_e32 v23, v47
	v_lshl_add_u64 v[22:23], s[12:13], 0, v[22:23]
	v_pk_add_f32 v[16:17], v[162:163], v[16:17]
	v_add_f32_e32 v58, v58, v59
	v_add_f32_e32 v44, v44, v45
	global_store_dwordx2 v[22:23], v[20:21], off
	v_mul_f32_e32 v20, v17, v17
	v_mul_f32_e32 v21, v19, v19
	v_add_f32_e32 v44, v58, v44
	v_add_f32_e32 v32, v32, v33
	v_fmac_f32_e32 v20, v16, v16
	v_fmac_f32_e32 v21, v18, v18
	v_add_f32_e32 v32, v44, v32
	v_add_f32_e32 v20, v20, v21
	v_add_f32_e32 v21, v32, v20
	ds_bpermute_b32 v22, v227, v21
	global_store_dwordx4 v[214:215], v[16:19], off offset:576
	v_or_b32_e32 v46, 0x120, v46
	v_readlane_b32 s61, v252, 17
	v_pk_mul_f32 v[16:17], v[0:1], v[16:17]
	v_pk_mul_f32 v[18:19], v[2:3], v[18:19]
	v_cvt_pk_bf16_f32 v20, v16, v17
	s_waitcnt lgkmcnt(0)
	v_add_f32_e32 v16, v21, v22
	ds_bpermute_b32 v17, v226, v16
	v_cvt_pk_bf16_f32 v21, v18, v19
	v_lshl_add_u64 v[18:19], s[12:13], 0, v[46:47]
	v_readlane_b32 s62, v252, 18
	v_readlane_b32 s63, v252, 19
	v_readlane_b32 s64, v252, 20
	v_readlane_b32 s65, v252, 21
	v_readlane_b32 s66, v252, 22
	v_readlane_b32 s67, v252, 23
	v_readlane_b32 s68, v252, 24
	v_readlane_b32 s69, v252, 25
	v_readlane_b32 s70, v252, 26
	v_readlane_b32 s71, v252, 27
	v_readlane_b32 s72, v252, 28
	v_readlane_b32 s73, v252, 29
	global_store_dwordx2 v[18:19], v[20:21], off
	s_and_saveexec_b64 s[24:25], s[2:3]
	s_cbranch_execz .LBB0_1066
	v_lshl_add_u64 v[18:19], v[212:213], 2, s[14:15]
	s_waitcnt lgkmcnt(0)
	v_add_f32_e32 v16, v16, v17
	global_atomic_add_f32 v[18:19], v16, off
.LBB0_1066:
	s_or_b64 exec, exec, s[24:25]
	s_waitcnt lgkmcnt(0)
	v_lshl_add_u64 v[16:17], v[144:145], 2, v[210:211]
	v_lshl_add_u64 v[162:163], v[16:17], 0, s[20:21]
	v_add_co_u32_e32 v16, vcc, 0x120000, v16
	v_lshlrev_b64 v[20:21], 11, v[194:195]
	s_nop 0
	v_addc_co_u32_e32 v17, vcc, 0, v17, vcc
	global_load_dwordx4 v[44:47], v[162:163], off offset:64 sc1
	global_load_dwordx4 v[32:35], v[162:163], off offset:512 sc1
	global_load_dwordx4 v[56:59], v[16:17], off sc1
	s_nop 0
	global_load_dwordx4 v[16:19], v[162:163], off offset:576 sc1
	v_lshl_add_u64 v[164:165], v[20:21], 0, v[144:145]
	s_waitcnt vmcnt(27)
	v_pk_add_f32 v[22:23], v[160:161], v[62:63]
	v_pk_add_f32 v[20:21], v[158:159], v[60:61]
	v_mul_f32_e32 v61, v23, v23
	v_mul_f32_e32 v60, v21, v21
	v_fmac_f32_e32 v60, v20, v20
	v_fmac_f32_e32 v61, v22, v22
	global_store_dwordx4 v[196:197], v[20:23], off
	v_add_f32_e32 v62, v60, v61
	v_lshlrev_b64 v[60:61], 1, v[164:165]
	v_pk_mul_f32 v[22:23], v[14:15], v[22:23]
	v_pk_mul_f32 v[20:21], v[12:13], v[20:21]
	s_nop 0
	v_cvt_pk_bf16_f32 v20, v20, v21
	v_cvt_pk_bf16_f32 v21, v22, v23
	v_lshl_add_u64 v[22:23], s[12:13], 0, v[60:61]
	global_store_dwordx2 v[22:23], v[20:21], off
	s_waitcnt vmcnt(28)
	v_pk_add_f32 v[22:23], v[156:157], v[54:55]
	v_pk_add_f32 v[20:21], v[154:155], v[52:53]
	v_mul_f32_e32 v53, v23, v23
	v_mul_f32_e32 v52, v21, v21
	global_store_dwordx4 v[196:197], v[20:23], off offset:64
	v_fmac_f32_e32 v52, v20, v20
	v_fmac_f32_e32 v53, v22, v22
	v_pk_mul_f32 v[22:23], v[10:11], v[22:23]
	v_pk_mul_f32 v[20:21], v[8:9], v[20:21]
	v_add_f32_e32 v52, v52, v53
	v_cvt_pk_bf16_f32 v20, v20, v21
	v_cvt_pk_bf16_f32 v21, v22, v23
	v_or_b32_e32 v22, 32, v60
	v_mov_b32_e32 v23, v61
	v_lshl_add_u64 v[22:23], s[12:13], 0, v[22:23]
	global_store_dwordx2 v[22:23], v[20:21], off
	s_waitcnt vmcnt(29)
	v_pk_add_f32 v[22:23], v[152:153], v[42:43]
	v_pk_add_f32 v[20:21], v[150:151], v[40:41]
	v_mul_f32_e32 v41, v23, v23
	v_mul_f32_e32 v40, v21, v21
	global_store_dwordx4 v[196:197], v[20:23], off offset:512
	v_fmac_f32_e32 v40, v20, v20
	v_fmac_f32_e32 v41, v22, v22
	v_pk_mul_f32 v[22:23], v[6:7], v[22:23]
	v_pk_mul_f32 v[20:21], v[4:5], v[20:21]
	v_add_f32_e32 v52, v62, v52
	v_cvt_pk_bf16_f32 v20, v20, v21
	v_cvt_pk_bf16_f32 v21, v22, v23
	v_or_b32_e32 v22, 0x100, v60
	v_mov_b32_e32 v23, v61
	v_lshl_add_u64 v[22:23], s[12:13], 0, v[22:23]
	global_store_dwordx2 v[22:23], v[20:21], off
	s_waitcnt vmcnt(30)
	v_pk_add_f32 v[22:23], v[148:149], v[30:31]
	v_pk_add_f32 v[20:21], v[146:147], v[28:29]
	v_mul_f32_e32 v29, v23, v23
	v_mul_f32_e32 v28, v21, v21
	v_add_f32_e32 v40, v40, v41
	v_fmac_f32_e32 v28, v20, v20
	v_fmac_f32_e32 v29, v22, v22
	v_add_f32_e32 v40, v52, v40
	v_add_f32_e32 v28, v28, v29
	v_add_f32_e32 v29, v40, v28
	ds_bpermute_b32 v30, v227, v29
	global_store_dwordx4 v[196:197], v[20:23], off offset:576
	v_or_b32_e32 v60, 0x120, v60
	s_nop 0
	v_pk_mul_f32 v[20:21], v[0:1], v[20:21]
	v_pk_mul_f32 v[22:23], v[2:3], v[22:23]
	v_cvt_pk_bf16_f32 v28, v20, v21
	s_waitcnt lgkmcnt(0)
	v_add_f32_e32 v20, v29, v30
	ds_bpermute_b32 v21, v226, v20
	v_cvt_pk_bf16_f32 v29, v22, v23
	v_lshl_add_u64 v[22:23], s[12:13], 0, v[60:61]
	global_store_dwordx2 v[22:23], v[28:29], off
	s_and_saveexec_b64 s[24:25], s[2:3]
	s_cbranch_execz .LBB0_1068
	v_lshl_add_u64 v[22:23], v[194:195], 2, s[14:15]
	s_waitcnt lgkmcnt(0)
	v_add_f32_e32 v20, v20, v21
	global_atomic_add_f32 v[22:23], v20, off
.LBB0_1068:
	s_or_b64 exec, exec, s[24:25]
	v_or_b32_e32 v146, 32, v178
	v_ashrrev_i32_e32 v147, 31, v146
	v_readlane_b32 s60, v252, 16
	s_waitcnt lgkmcnt(0)
	v_lshlrev_b64 v[20:21], 13, v[146:147]
	v_readlane_b32 s74, v252, 30
	v_readlane_b32 s75, v252, 31
	v_lshlrev_b64 v[60:61], 11, v[178:179]
	v_lshl_add_u64 v[150:151], v[60:61], 0, v[144:145]
	v_lshl_add_u64 v[20:21], s[74:75], 0, v[20:21]
	v_lshl_add_u64 v[148:149], v[144:145], 2, v[20:21]
	global_load_dwordx4 v[52:55], v[148:149], off sc1
	global_load_dwordx4 v[40:43], v[148:149], off offset:64 sc1
	global_load_dwordx4 v[28:31], v[148:149], off offset:512 sc1
	global_load_dwordx4 v[20:23], v[148:149], off offset:576 sc1
	s_waitcnt vmcnt(27)
	v_pk_add_f32 v[62:63], v[142:143], v[66:67]
	v_pk_add_f32 v[60:61], v[140:141], v[64:65]
	v_mul_f32_e32 v65, v63, v63
	v_mul_f32_e32 v64, v61, v61
	global_store_dwordx4 v[180:181], v[60:63], off
	v_fmac_f32_e32 v64, v60, v60
	v_fmac_f32_e32 v65, v62, v62
	v_pk_mul_f32 v[62:63], v[14:15], v[62:63]
	v_pk_mul_f32 v[60:61], v[12:13], v[60:61]
	v_add_f32_e32 v66, v64, v65
	v_cvt_pk_bf16_f32 v60, v60, v61
	v_cvt_pk_bf16_f32 v61, v62, v63
	v_lshlrev_b64 v[62:63], 1, v[150:151]
	v_lshl_add_u64 v[64:65], s[12:13], 0, v[62:63]
	s_waitcnt vmcnt(27)
	v_pk_add_f32 v[50:51], v[126:127], v[50:51]
	v_pk_add_f32 v[48:49], v[124:125], v[48:49]
	global_store_dwordx2 v[64:65], v[60:61], off
	v_mul_f32_e32 v60, v49, v49
	v_mul_f32_e32 v61, v51, v51
	global_store_dwordx4 v[180:181], v[48:51], off offset:64
	v_fmac_f32_e32 v60, v48, v48
	v_fmac_f32_e32 v61, v50, v50
	v_pk_mul_f32 v[50:51], v[10:11], v[50:51]
	v_pk_mul_f32 v[48:49], v[8:9], v[48:49]
	s_waitcnt vmcnt(28)
	v_pk_add_f32 v[38:39], v[122:123], v[38:39]
	v_cvt_pk_bf16_f32 v48, v48, v49
	v_cvt_pk_bf16_f32 v49, v50, v51
	v_or_b32_e32 v50, 32, v62
	v_mov_b32_e32 v51, v63
	v_lshl_add_u64 v[50:51], s[12:13], 0, v[50:51]
	v_pk_add_f32 v[36:37], v[120:121], v[36:37]
	global_store_dwordx2 v[50:51], v[48:49], off
	v_mul_f32_e32 v48, v37, v37
	v_mul_f32_e32 v49, v39, v39
	global_store_dwordx4 v[180:181], v[36:39], off offset:512
	v_fmac_f32_e32 v48, v36, v36
	v_fmac_f32_e32 v49, v38, v38
	v_pk_mul_f32 v[38:39], v[6:7], v[38:39]
	v_pk_mul_f32 v[36:37], v[4:5], v[36:37]
	s_waitcnt vmcnt(29)
	v_pk_add_f32 v[26:27], v[118:119], v[26:27]
	v_cvt_pk_bf16_f32 v36, v36, v37
	v_cvt_pk_bf16_f32 v37, v38, v39
	v_or_b32_e32 v38, 0x100, v62
	v_mov_b32_e32 v39, v63
	v_lshl_add_u64 v[38:39], s[12:13], 0, v[38:39]
	v_pk_add_f32 v[24:25], v[116:117], v[24:25]
	v_add_f32_e32 v60, v60, v61
	global_store_dwordx2 v[38:39], v[36:37], off
	v_mul_f32_e32 v36, v25, v25
	v_mul_f32_e32 v37, v27, v27
	v_add_f32_e32 v60, v66, v60
	v_add_f32_e32 v48, v48, v49
	v_fmac_f32_e32 v36, v24, v24
	v_fmac_f32_e32 v37, v26, v26
	v_add_f32_e32 v48, v60, v48
	v_add_f32_e32 v36, v36, v37
	v_add_f32_e32 v37, v48, v36
	ds_bpermute_b32 v38, v227, v37
	global_store_dwordx4 v[180:181], v[24:27], off offset:576
	v_or_b32_e32 v62, 0x120, v62
	v_readlane_b32 s61, v252, 17
	v_pk_mul_f32 v[24:25], v[0:1], v[24:25]
	v_pk_mul_f32 v[26:27], v[2:3], v[26:27]
	v_cvt_pk_bf16_f32 v36, v24, v25
	s_waitcnt lgkmcnt(0)
	v_add_f32_e32 v24, v37, v38
	ds_bpermute_b32 v25, v226, v24
	v_cvt_pk_bf16_f32 v37, v26, v27
	v_lshl_add_u64 v[26:27], s[12:13], 0, v[62:63]
	v_readlane_b32 s62, v252, 18
	v_readlane_b32 s63, v252, 19
	v_readlane_b32 s64, v252, 20
	v_readlane_b32 s65, v252, 21
	v_readlane_b32 s66, v252, 22
	v_readlane_b32 s67, v252, 23
	v_readlane_b32 s68, v252, 24
	v_readlane_b32 s69, v252, 25
	v_readlane_b32 s70, v252, 26
	v_readlane_b32 s71, v252, 27
	v_readlane_b32 s72, v252, 28
	v_readlane_b32 s73, v252, 29
	global_store_dwordx2 v[26:27], v[36:37], off
	s_and_saveexec_b64 s[24:25], s[2:3]
	s_cbranch_execz .LBB0_1070
	v_lshl_add_u64 v[26:27], v[178:179], 2, s[14:15]
	s_waitcnt lgkmcnt(0)
	v_add_f32_e32 v24, v24, v25
	global_atomic_add_f32 v[26:27], v24, off
.LBB0_1070:
	s_or_b64 exec, exec, s[24:25]
	v_or_b32_e32 v64, 48, v178
	v_ashrrev_i32_e32 v65, 31, v64
	v_readlane_b32 s60, v252, 16
	s_waitcnt lgkmcnt(0)
	v_lshlrev_b64 v[24:25], 13, v[64:65]
	v_readlane_b32 s74, v252, 30
	v_readlane_b32 s75, v252, 31
	v_or_b32_e32 v116, 16, v178
	v_ashrrev_i32_e32 v117, 31, v116
	v_lshl_add_u64 v[24:25], s[74:75], 0, v[24:25]
	v_lshl_add_u64 v[66:67], v[144:145], 2, v[24:25]
	global_load_dwordx4 v[60:63], v[66:67], off sc1
	global_load_dwordx4 v[48:51], v[66:67], off offset:64 sc1
	global_load_dwordx4 v[36:39], v[66:67], off offset:512 sc1
	global_load_dwordx4 v[24:27], v[66:67], off offset:576 sc1
	s_waitcnt vmcnt(25)
	v_pk_add_f32 v[58:59], v[114:115], v[58:59]
	v_pk_add_f32 v[56:57], v[112:113], v[56:57]
	v_lshlrev_b64 v[118:119], 11, v[116:117]
	v_mul_f32_e32 v112, v57, v57
	v_mul_f32_e32 v113, v59, v59
	v_lshl_add_u64 v[118:119], v[118:119], 0, v[144:145]
	global_store_dwordx4 v[162:163], v[56:59], off
	v_fmac_f32_e32 v112, v56, v56
	v_fmac_f32_e32 v113, v58, v58
	v_pk_mul_f32 v[58:59], v[14:15], v[58:59]
	v_pk_mul_f32 v[56:57], v[12:13], v[56:57]
	v_add_f32_e32 v114, v112, v113
	v_cvt_pk_bf16_f32 v56, v56, v57
	v_cvt_pk_bf16_f32 v57, v58, v59
	v_lshlrev_b64 v[58:59], 1, v[118:119]
	v_lshl_add_u64 v[112:113], s[12:13], 0, v[58:59]
	v_pk_add_f32 v[46:47], v[110:111], v[46:47]
	v_pk_add_f32 v[44:45], v[108:109], v[44:45]
	global_store_dwordx2 v[112:113], v[56:57], off
	v_mul_f32_e32 v56, v45, v45
	v_mul_f32_e32 v57, v47, v47
	global_store_dwordx4 v[162:163], v[44:47], off offset:64
	v_fmac_f32_e32 v56, v44, v44
	v_fmac_f32_e32 v57, v46, v46
	v_pk_mul_f32 v[46:47], v[10:11], v[46:47]
	v_pk_mul_f32 v[44:45], v[8:9], v[44:45]
	v_pk_add_f32 v[34:35], v[106:107], v[34:35]
	v_cvt_pk_bf16_f32 v44, v44, v45
	v_cvt_pk_bf16_f32 v45, v46, v47
	v_or_b32_e32 v46, 32, v58
	v_mov_b32_e32 v47, v59
	v_lshl_add_u64 v[46:47], s[12:13], 0, v[46:47]
	v_pk_add_f32 v[32:33], v[104:105], v[32:33]
	global_store_dwordx2 v[46:47], v[44:45], off
	v_mul_f32_e32 v44, v33, v33
	v_mul_f32_e32 v45, v35, v35
	global_store_dwordx4 v[162:163], v[32:35], off offset:512
	v_fmac_f32_e32 v44, v32, v32
	v_fmac_f32_e32 v45, v34, v34
	v_pk_mul_f32 v[34:35], v[6:7], v[34:35]
	v_pk_mul_f32 v[32:33], v[4:5], v[32:33]
	s_waitcnt vmcnt(29)
	v_pk_add_f32 v[18:19], v[102:103], v[18:19]
	v_cvt_pk_bf16_f32 v32, v32, v33
	v_cvt_pk_bf16_f32 v33, v34, v35
	v_or_b32_e32 v34, 0x100, v58
	v_mov_b32_e32 v35, v59
	v_lshl_add_u64 v[34:35], s[12:13], 0, v[34:35]
	v_pk_add_f32 v[16:17], v[100:101], v[16:17]
	v_add_f32_e32 v56, v56, v57
	global_store_dwordx2 v[34:35], v[32:33], off
	v_mul_f32_e32 v32, v17, v17
	v_mul_f32_e32 v33, v19, v19
	v_add_f32_e32 v56, v114, v56
	v_add_f32_e32 v44, v44, v45
	v_fmac_f32_e32 v32, v16, v16
	v_fmac_f32_e32 v33, v18, v18
	v_add_f32_e32 v44, v56, v44
	v_add_f32_e32 v32, v32, v33
	v_add_f32_e32 v33, v44, v32
	ds_bpermute_b32 v34, v227, v33
	global_store_dwordx4 v[162:163], v[16:19], off offset:576
	v_or_b32_e32 v58, 0x120, v58
	v_readlane_b32 s61, v252, 17
	v_pk_mul_f32 v[16:17], v[0:1], v[16:17]
	v_pk_mul_f32 v[18:19], v[2:3], v[18:19]
	v_cvt_pk_bf16_f32 v32, v16, v17
	s_waitcnt lgkmcnt(0)
	v_add_f32_e32 v16, v33, v34
	ds_bpermute_b32 v17, v226, v16
	v_cvt_pk_bf16_f32 v33, v18, v19
	v_lshl_add_u64 v[18:19], s[12:13], 0, v[58:59]
	v_readlane_b32 s62, v252, 18
	v_readlane_b32 s63, v252, 19
	v_readlane_b32 s64, v252, 20
	v_readlane_b32 s65, v252, 21
	v_readlane_b32 s66, v252, 22
	v_readlane_b32 s67, v252, 23
	v_readlane_b32 s68, v252, 24
	v_readlane_b32 s69, v252, 25
	v_readlane_b32 s70, v252, 26
	v_readlane_b32 s71, v252, 27
	v_readlane_b32 s72, v252, 28
	v_readlane_b32 s73, v252, 29
	global_store_dwordx2 v[18:19], v[32:33], off
	s_and_saveexec_b64 s[24:25], s[2:3]
	s_cbranch_execz .LBB0_1072
	v_lshl_add_u64 v[18:19], v[116:117], 2, s[14:15]
	s_waitcnt lgkmcnt(0)
	v_add_f32_e32 v16, v16, v17
	global_atomic_add_f32 v[18:19], v16, off
